# P9 conv epilogue: 50 boundary taps (select with zero + row rotate) folded into one DPP row shift with zero fill
# speedup vs baseline: 1.0029x; 1.0003x over previous
; __device__ __forceinline__ void st_bf4(bf16_t* p, f32x4 v) { u32x2 w; w.x = pk2(v[0], v[1]); w.y = pk2(v[2], v[3]); *(u32x2*)p = w; }
; __device__ __forceinline__ float sigmoidf_(float x) { return __builtin_amdgcn_rcpf(1.f + __expf(-x)); }
; __device__ __forceinline__ float dpp_ror1(float v) { return __int_as_float(__builtin_amdgcn_update_dpp(0, __float_as_int(v), 0x121, 0xf, 0xf, false)); }
; __device__ __forceinline__ float dpp_rol1(float v) { return __int_as_float(__builtin_amdgcn_update_dpp(0, __float_as_int(v), 0x12F, 0xf, 0xf, false)); }
;     __device__ __forceinline__ void tile(const f32x4 (&acc)[2][2][4][2], const Unit& u, int wr, int wc, int fr, int fq) const {
; #pragma unroll
;         for (int n = 0; n < 2; ++n) {
;             const int cv = 128 * u.pn + 32 * wc + 16 * n + 4 * fq, cg = FF + cv;
;             const f32x4 wv0 = *(const f32x4*)(cw + cv), wv1 = *(const f32x4*)(cw + F2 + cv), wv2 = *(const f32x4*)(cw + 2 * F2 + cv), bv = *(const f32x4*)(cb + cv);
;             const f32x4 wg0 = *(const f32x4*)(cw + cg), wg1 = *(const f32x4*)(cw + F2 + cg), wg2 = *(const f32x4*)(cw + 2 * F2 + cg), bg = *(const f32x4*)(cb + cg);
; #pragma unroll
;             for (int ai = 0; ai < 2; ++ai)
; #pragma unroll
;                 for (int m = 0; m < 4; ++m) {
;                     f32x4 r;
; #pragma unroll
;                     for (int i = 0; i < 4; ++i) {
;                         const float xv = acc[ai][0][m][n][i], xg = acc[ai][1][m][n][i];
;                         const float uv = m > 0 ? acc[ai][0][m > 0 ? m - 1 : 0][n][i] : 0.f, ug = m > 0 ? acc[ai][1][m > 0 ? m - 1 : 0][n][i] : 0.f;
;                         const float dv = m < 3 ? acc[ai][0][m < 3 ? m + 1 : 3][n][i] : 0.f, dg = m < 3 ? acc[ai][1][m < 3 ? m + 1 : 3][n][i] : 0.f;
;                         const float pv = dpp_ror1(fr == 15 ? uv : xv), pg = dpp_ror1(fr == 15 ? ug : xg);
;                         const float nv = dpp_rol1(fr == 0 ? dv : xv), ng = dpp_rol1(fr == 0 ? dg : xg);
;                         const float yv = wv0[i] * pv + wv1[i] * xv + wv2[i] * nv + bv[i];
;                         const float yg = wg0[i] * pg + wg1[i] * xg + wg2[i] * ng + bg[i];
;                         r[i] = yg * sigmoidf_(yg) * yv;
;                     }
;                     st_bf4(ACT + (size_t)(u.pm * BM + ai * HALF + wr * 64 + m * 16 + fr) * FF + cv, r);
.LBB0_1802:
	v_lshl_or_b32 v170, s33, 7, v204
	v_ashrrev_i32_e32 v171, 31, v170
	v_lshlrev_b64 v[120:121], 2, v[170:171]
	v_lshl_add_u64 v[172:173], s[56:57], 0, v[120:121]
	v_add_co_u32_e32 v176, vcc, 0x5000, v172
	v_lshl_add_u64 v[122:123], s[12:13], 0, v[120:121]
	s_nop 0
	v_addc_co_u32_e32 v177, vcc, 0, v173, vcc
	v_add_co_u32_e32 v178, vcc, 0x5000, v122
	v_lshl_add_u64 v[124:125], s[14:15], 0, v[120:121]
	s_nop 0
	v_addc_co_u32_e32 v179, vcc, 0, v123, vcc
	global_load_dwordx4 v[132:135], v[176:177], off offset:2048
	global_load_dwordx4 v[148:151], v[178:179], off offset:2048
	v_add_co_u32_e32 v180, vcc, 0x5000, v124
	v_lshl_add_u64 v[174:175], s[58:59], 0, v[120:121]
	s_nop 0
	v_addc_co_u32_e32 v181, vcc, 0, v125, vcc
	global_load_dwordx4 v[136:139], v[180:181], off offset:2048
	v_add_co_u32_e32 v182, vcc, 0x5000, v174
	s_nop 0
	v_addc_co_u32_e32 v183, vcc, 0, v175, vcc
	global_load_dwordx4 v[140:143], v[182:183], off offset:2048
	global_load_dwordx4 v[230:233], v[176:177], off offset:2112
	global_load_dwordx4 v[234:237], v[178:179], off offset:2112
	global_load_dwordx4 v[238:241], v[180:181], off offset:2112
	global_load_dwordx4 v[242:245], v[182:183], off offset:2112
	global_load_dwordx4 v[246:249], v[122:123], off offset:64
	global_load_dwordx4 v[144:147], v[122:123], off
	s_nop 0
	global_load_dwordx4 v[250:253], v[172:173], off offset:64
	global_load_dwordx4 v[120:123], v[172:173], off
	s_nop 0
	global_load_dwordx4 v[190:193], v[124:125], off offset:64
	global_load_dwordx4 v[124:127], v[124:125], off
	s_nop 0
	global_load_dwordx4 v[128:131], v[174:175], off
	s_nop 0
	global_load_dwordx4 v[180:183], v[174:175], off offset:64
	v_mov_b32_dpp v208, v156 row_shr:1 row_mask:0xf bank_mask:0xf bound_ctrl:1
	v_mov_b32_dpp v168, v152 row_shr:1 row_mask:0xf bank_mask:0xf bound_ctrl:1
	v_cndmask_b32_e64 v169, v156, v116, s[6:7]
	s_nop 1
	v_mov_b32_dpp v210, v169 row_ror:15 row_mask:0xf bank_mask:0xf
	v_cndmask_b32_e64 v169, v152, v112, s[6:7]
	s_nop 1
	v_mov_b32_dpp v186, v169 row_ror:15 row_mask:0xf bank_mask:0xf
	v_mov_b32_dpp v209, v157 row_shr:1 row_mask:0xf bank_mask:0xf bound_ctrl:1
	v_mov_b32_dpp v169, v153 row_shr:1 row_mask:0xf bank_mask:0xf bound_ctrl:1
	v_cndmask_b32_e64 v184, v157, v117, s[6:7]
	s_nop 1
	v_mov_b32_dpp v211, v184 row_ror:15 row_mask:0xf bank_mask:0xf
	v_cndmask_b32_e64 v184, v153, v113, s[6:7]
	s_lshl_b32 s17, s26, 8
	s_nop 0
	v_mov_b32_dpp v187, v184 row_ror:15 row_mask:0xf bank_mask:0xf
	v_add_u32_e32 v220, s17, v195
	s_andn2_b64 vcc, exec, s[20:21]
	v_mov_b32_dpp v212, v158 row_shr:1 row_mask:0xf bank_mask:0xf bound_ctrl:1
	s_mov_b64 s[20:21], -1
	s_waitcnt vmcnt(0)
	v_pk_mul_f32 v[222:223], v[152:153], v[148:149]
	s_nop 0
	v_pk_fma_f32 v[168:169], v[132:133], v[168:169], v[222:223]
	v_mov_b32_dpp v214, v154 row_shr:1 row_mask:0xf bank_mask:0xf bound_ctrl:1
	v_cndmask_b32_e64 v184, v158, v118, s[6:7]
	v_pk_fma_f32 v[168:169], v[136:137], v[186:187], v[168:169]
	v_lshlrev_b64 v[186:187], 1, v[170:171]
	v_pk_add_f32 v[222:223], v[140:141], v[168:169]
	v_mov_b32_dpp v216, v184 row_ror:15 row_mask:0xf bank_mask:0xf
	v_mul_f32_e32 v168, 0xbfb8aa3b, v222
	v_exp_f32_e32 v224, v168
	v_cndmask_b32_e64 v184, v154, v114, s[6:7]
	v_pk_mul_f32 v[228:229], v[156:157], v[144:145]
	v_pk_mul_f32 v[226:227], v[158:159], v[146:147]
	v_add_f32_e32 v171, 1.0, v224
	v_mul_f32_e32 v224, 0xbfb8aa3b, v223
	v_exp_f32_e32 v225, v224
	v_mov_b32_dpp v218, v184 row_ror:15 row_mask:0xf bank_mask:0xf
	v_rcp_f32_e32 v224, v171
	v_add_f32_e32 v171, 1.0, v225
	v_mov_b32_dpp v213, v159 row_shr:1 row_mask:0xf bank_mask:0xf bound_ctrl:1
	v_rcp_f32_e32 v225, v171
	v_pk_fma_f32 v[208:209], v[120:121], v[208:209], v[228:229]
	v_mov_b32_dpp v215, v155 row_shr:1 row_mask:0xf bank_mask:0xf bound_ctrl:1
	v_cndmask_b32_e64 v184, v159, v119, s[6:7]
	v_pk_fma_f32 v[208:209], v[124:125], v[210:211], v[208:209]
	v_pk_mul_f32 v[210:211], v[222:223], v[224:225]
	v_mov_b32_dpp v217, v184 row_ror:15 row_mask:0xf bank_mask:0xf
	v_cndmask_b32_e64 v184, v155, v115, s[6:7]
	v_pk_add_f32 v[208:209], v[128:129], v[208:209]
	v_pk_fma_f32 v[212:213], v[122:123], v[212:213], v[226:227]
	v_mov_b32_dpp v219, v184 row_ror:15 row_mask:0xf bank_mask:0xf
	v_mov_b64_e32 v[184:185], s[0:1]
	v_mad_i64_i32 v[220:221], s[28:29], v220, s46, v[184:185]
	v_lshl_add_u64 v[168:169], v[220:221], 0, v[186:187]
	v_pk_mul_f32 v[220:221], v[154:155], v[150:151]
	v_pk_mul_f32 v[208:209], v[208:209], v[210:211]
	v_pk_fma_f32 v[210:211], v[134:135], v[214:215], v[220:221]
	v_pk_fma_f32 v[212:213], v[126:127], v[216:217], v[212:213]
	v_pk_fma_f32 v[210:211], v[138:139], v[218:219], v[210:211]
	v_pk_add_f32 v[212:213], v[130:131], v[212:213]
	v_pk_add_f32 v[210:211], v[142:143], v[210:211]
	v_cvt_pk_bf16_f32 v208, v208, v209
	v_mul_f32_e32 v171, 0xbfb8aa3b, v210
	v_exp_f32_e32 v171, v171
	v_mul_f32_e32 v214, 0xbfb8aa3b, v211
	v_exp_f32_e32 v215, v214
	v_pk_mul_f32 v[216:217], v[112:113], v[148:149]
	v_add_f32_e32 v171, 1.0, v171
	v_rcp_f32_e32 v214, v171
	v_add_f32_e32 v171, 1.0, v215
	v_rcp_f32_e32 v215, v171
	v_cndmask_b32_e64 v171, v116, v156, s[4:5]
	v_pk_mul_f32 v[222:223], v[116:117], v[144:145]
	v_pk_mul_f32 v[210:211], v[210:211], v[214:215]
	v_mov_b32_dpp v156, v171 row_ror:1 row_mask:0xf bank_mask:0xf
	v_pk_mul_f32 v[210:211], v[212:213], v[210:211]
	v_cndmask_b32_e64 v171, v112, v152, s[4:5]
	v_cvt_pk_bf16_f32 v209, v210, v211
	global_store_dwordx2 v[168:169], v[208:209], off
	v_mov_b32_dpp v152, v171 row_ror:1 row_mask:0xf bank_mask:0xf
	v_cndmask_b32_e64 v171, v116, v108, s[6:7]
	s_nop 1
	v_mov_b32_dpp v208, v171 row_ror:15 row_mask:0xf bank_mask:0xf
	v_cndmask_b32_e64 v171, v112, v104, s[6:7]
; __device__ __forceinline__ void st_bf4(bf16_t* p, f32x4 v) { u32x2 w; w.x = pk2(v[0], v[1]); w.y = pk2(v[2], v[3]); *(u32x2*)p = w; }
; __device__ __forceinline__ float sigmoidf_(float x) { return __builtin_amdgcn_rcpf(1.f + __expf(-x)); }
; __device__ __forceinline__ float dpp_ror1(float v) { return __int_as_float(__builtin_amdgcn_update_dpp(0, __float_as_int(v), 0x121, 0xf, 0xf, false)); }
; __device__ __forceinline__ float dpp_rol1(float v) { return __int_as_float(__builtin_amdgcn_update_dpp(0, __float_as_int(v), 0x12F, 0xf, 0xf, false)); }
;     __device__ __forceinline__ void tile(const f32x4 (&acc)[2][2][4][2], const Unit& u, int wr, int wc, int fr, int fq) const {
;     ...
;                         const float xv = acc[ai][0][m][n][i], xg = acc[ai][1][m][n][i];
;                         const float uv = m > 0 ? acc[ai][0][m > 0 ? m - 1 : 0][n][i] : 0.f, ug = m > 0 ? acc[ai][1][m > 0 ? m - 1 : 0][n][i] : 0.f;
;                         const float dv = m < 3 ? acc[ai][0][m < 3 ? m + 1 : 3][n][i] : 0.f, dg = m < 3 ? acc[ai][1][m < 3 ? m + 1 : 3][n][i] : 0.f;
;                         const float pv = dpp_ror1(fr == 15 ? uv : xv), pg = dpp_ror1(fr == 15 ? ug : xg);
;                         const float nv = dpp_rol1(fr == 0 ? dv : xv), ng = dpp_rol1(fr == 0 ? dg : xg);
;                         const float yv = wv0[i] * pv + wv1[i] * xv + wv2[i] * nv + bv[i];
;                         const float yg = wg0[i] * pg + wg1[i] * xg + wg2[i] * ng + bg[i];
;                         r[i] = yg * sigmoidf_(yg) * yv;
;                     }
;                     st_bf4(ACT + (size_t)(u.pm * BM + ai * HALF + wr * 64 + m * 16 + fr) * FF + cv, r);
	s_nop 1
	v_mov_b32_dpp v210, v171 row_ror:15 row_mask:0xf bank_mask:0xf
	v_cndmask_b32_e64 v171, v117, v157, s[4:5]
	s_nop 1
	v_mov_b32_dpp v157, v171 row_ror:1 row_mask:0xf bank_mask:0xf
	v_cndmask_b32_e64 v171, v113, v153, s[4:5]
	v_pk_fma_f32 v[156:157], v[120:121], v[156:157], v[222:223]
	s_nop 0
	v_mov_b32_dpp v153, v171 row_ror:1 row_mask:0xf bank_mask:0xf
	v_cndmask_b32_e64 v171, v117, v109, s[6:7]
	v_pk_fma_f32 v[152:153], v[132:133], v[152:153], v[216:217]
	v_pk_mul_f32 v[216:217], v[114:115], v[150:151]
	v_mov_b32_dpp v209, v171 row_ror:15 row_mask:0xf bank_mask:0xf
	v_cndmask_b32_e64 v171, v113, v105, s[6:7]
	v_pk_fma_f32 v[156:157], v[124:125], v[208:209], v[156:157]
	v_pk_mul_f32 v[220:221], v[118:119], v[146:147]
	v_mov_b32_dpp v211, v171 row_ror:15 row_mask:0xf bank_mask:0xf
	v_cndmask_b32_e64 v171, v118, v158, s[4:5]
	v_pk_fma_f32 v[152:153], v[136:137], v[210:211], v[152:153]
	v_pk_add_f32 v[156:157], v[128:129], v[156:157]
	v_mov_b32_dpp v158, v171 row_ror:1 row_mask:0xf bank_mask:0xf
	v_cndmask_b32_e64 v171, v114, v154, s[4:5]
	v_pk_add_f32 v[210:211], v[140:141], v[152:153]
	s_nop 0
	v_mov_b32_dpp v154, v171 row_ror:1 row_mask:0xf bank_mask:0xf
	v_cndmask_b32_e64 v171, v118, v110, s[6:7]
	v_mul_f32_e32 v152, 0xbfb8aa3b, v210
	v_exp_f32_e32 v218, v152
	v_mov_b32_dpp v212, v171 row_ror:15 row_mask:0xf bank_mask:0xf
	v_cndmask_b32_e64 v171, v114, v106, s[6:7]
	s_nop 1
	v_mov_b32_dpp v214, v171 row_ror:15 row_mask:0xf bank_mask:0xf
	v_cndmask_b32_e64 v171, v119, v159, s[4:5]
	s_nop 1
	v_mov_b32_dpp v159, v171 row_ror:1 row_mask:0xf bank_mask:0xf
	v_cndmask_b32_e64 v171, v115, v155, s[4:5]
	v_pk_fma_f32 v[158:159], v[122:123], v[158:159], v[220:221]
	s_nop 0
	v_mov_b32_dpp v155, v171 row_ror:1 row_mask:0xf bank_mask:0xf
	v_cndmask_b32_e64 v171, v119, v111, s[6:7]
	v_pk_fma_f32 v[154:155], v[134:135], v[154:155], v[216:217]
	v_pk_mul_f32 v[216:217], v[108:109], v[144:145]
	v_mov_b32_dpp v213, v171 row_ror:15 row_mask:0xf bank_mask:0xf
	v_cndmask_b32_e64 v171, v115, v107, s[6:7]
	v_pk_fma_f32 v[158:159], v[126:127], v[212:213], v[158:159]
	s_nop 0
	v_mov_b32_dpp v215, v171 row_ror:15 row_mask:0xf bank_mask:0xf
	v_add_u32_e32 v171, s17, v197
	v_mad_i64_i32 v[152:153], s[28:29], v171, s46, v[184:185]
	v_add_f32_e32 v171, 1.0, v218
	v_mul_f32_e32 v218, 0xbfb8aa3b, v211
	v_exp_f32_e32 v219, v218
	v_rcp_f32_e32 v218, v171
	v_pk_fma_f32 v[154:155], v[138:139], v[214:215], v[154:155]
	v_pk_add_f32 v[158:159], v[130:131], v[158:159]
	v_add_f32_e32 v171, 1.0, v219
	v_rcp_f32_e32 v219, v171
	v_pk_add_f32 v[154:155], v[142:143], v[154:155]
	v_lshl_add_u64 v[152:153], v[152:153], 0, v[186:187]
	v_mul_f32_e32 v171, 0xbfb8aa3b, v154
	v_pk_mul_f32 v[208:209], v[210:211], v[218:219]
	v_exp_f32_e32 v171, v171
	v_pk_mul_f32 v[156:157], v[156:157], v[208:209]
	v_mul_f32_e32 v208, 0xbfb8aa3b, v155
	v_exp_f32_e32 v209, v208
	v_cvt_pk_bf16_f32 v156, v156, v157
	v_add_f32_e32 v157, 1.0, v171
	v_rcp_f32_e32 v208, v157
	v_add_f32_e32 v157, 1.0, v209
	v_rcp_f32_e32 v209, v157
	v_pk_mul_f32 v[210:211], v[104:105], v[148:149]
	v_cndmask_b32_e64 v171, v111, v103, s[6:7]
	v_pk_mul_f32 v[214:215], v[110:111], v[146:147]
	v_pk_mul_f32 v[154:155], v[154:155], v[208:209]
	s_nop 0
	v_pk_mul_f32 v[154:155], v[158:159], v[154:155]
	v_cndmask_b32_e64 v158, v105, v97, s[6:7]
	v_cvt_pk_bf16_f32 v157, v154, v155
	v_cndmask_b32_e64 v154, v108, v116, s[4:5]
	v_cndmask_b32_e64 v155, v108, v100, s[6:7]
	global_store_dwordx2 v[152:153], v[156:157], off
	v_mov_b32_dpp v116, v154 row_ror:1 row_mask:0xf bank_mask:0xf
	v_cndmask_b32_e64 v154, v104, v112, s[4:5]
	v_cndmask_b32_e64 v157, v109, v101, s[6:7]
	s_nop 0
	v_mov_b32_dpp v112, v154 row_ror:1 row_mask:0xf bank_mask:0xf
	v_cndmask_b32_e64 v159, v110, v102, s[6:7]
	v_mov_b32_dpp v154, v155 row_ror:15 row_mask:0xf bank_mask:0xf
	v_cndmask_b32_e64 v155, v104, v96, s[6:7]
	s_nop 1
	v_mov_b32_dpp v156, v155 row_ror:15 row_mask:0xf bank_mask:0xf
	v_cndmask_b32_e64 v155, v109, v117, s[4:5]
	s_nop 1
	v_mov_b32_dpp v117, v155 row_ror:1 row_mask:0xf bank_mask:0xf
	v_cndmask_b32_e64 v155, v105, v113, s[4:5]
	v_pk_fma_f32 v[116:117], v[120:121], v[116:117], v[216:217]
	s_nop 0
	v_mov_b32_dpp v113, v155 row_ror:1 row_mask:0xf bank_mask:0xf
	v_pk_fma_f32 v[112:113], v[132:133], v[112:113], v[210:211]
	v_pk_mul_f32 v[210:211], v[106:107], v[150:151]
	v_mov_b32_dpp v155, v157 row_ror:15 row_mask:0xf bank_mask:0xf
	v_pk_fma_f32 v[116:117], v[124:125], v[154:155], v[116:117]
	s_nop 0
	v_mov_b32_dpp v157, v158 row_ror:15 row_mask:0xf bank_mask:0xf
	v_cndmask_b32_e64 v158, v110, v118, s[4:5]
	v_pk_fma_f32 v[112:113], v[136:137], v[156:157], v[112:113]
	v_pk_add_f32 v[116:117], v[128:129], v[116:117]
	v_mov_b32_dpp v118, v158 row_ror:1 row_mask:0xf bank_mask:0xf
	v_cndmask_b32_e64 v158, v106, v114, s[4:5]
	v_pk_add_f32 v[156:157], v[140:141], v[112:113]
	s_nop 0
	v_mov_b32_dpp v114, v158 row_ror:1 row_mask:0xf bank_mask:0xf
	v_mul_f32_e32 v112, 0xbfb8aa3b, v156
	v_exp_f32_e32 v212, v112
	v_mov_b32_dpp v158, v159 row_ror:15 row_mask:0xf bank_mask:0xf
	v_cndmask_b32_e64 v159, v106, v98, s[6:7]
	s_nop 1
	v_mov_b32_dpp v208, v159 row_ror:15 row_mask:0xf bank_mask:0xf
	v_cndmask_b32_e64 v159, v111, v119, s[4:5]
	s_nop 1
	v_mov_b32_dpp v119, v159 row_ror:1 row_mask:0xf bank_mask:0xf
	v_cndmask_b32_e64 v159, v107, v115, s[4:5]
	v_pk_fma_f32 v[118:119], v[122:123], v[118:119], v[214:215]
	s_nop 0
	v_mov_b32_dpp v115, v159 row_ror:1 row_mask:0xf bank_mask:0xf
	v_pk_fma_f32 v[114:115], v[134:135], v[114:115], v[210:211]
	s_nop 0
	v_mov_b32_dpp v159, v171 row_ror:15 row_mask:0xf bank_mask:0xf
	v_cndmask_b32_e64 v171, v107, v99, s[6:7]
; __device__ __forceinline__ void st_bf4(bf16_t* p, f32x4 v) { u32x2 w; w.x = pk2(v[0], v[1]); w.y = pk2(v[2], v[3]); *(u32x2*)p = w; }
; __device__ __forceinline__ float sigmoidf_(float x) { return __builtin_amdgcn_rcpf(1.f + __expf(-x)); }
; __device__ __forceinline__ float dpp_ror1(float v) { return __int_as_float(__builtin_amdgcn_update_dpp(0, __float_as_int(v), 0x121, 0xf, 0xf, false)); }
; __device__ __forceinline__ float dpp_rol1(float v) { return __int_as_float(__builtin_amdgcn_update_dpp(0, __float_as_int(v), 0x12F, 0xf, 0xf, false)); }
;     __device__ __forceinline__ void tile(const f32x4 (&acc)[2][2][4][2], const Unit& u, int wr, int wc, int fr, int fq) const {
;     ...
;                         const float xv = acc[ai][0][m][n][i], xg = acc[ai][1][m][n][i];
;                         const float uv = m > 0 ? acc[ai][0][m > 0 ? m - 1 : 0][n][i] : 0.f, ug = m > 0 ? acc[ai][1][m > 0 ? m - 1 : 0][n][i] : 0.f;
;                         const float dv = m < 3 ? acc[ai][0][m < 3 ? m + 1 : 3][n][i] : 0.f, dg = m < 3 ? acc[ai][1][m < 3 ? m + 1 : 3][n][i] : 0.f;
;                         const float pv = dpp_ror1(fr == 15 ? uv : xv), pg = dpp_ror1(fr == 15 ? ug : xg);
;                         const float nv = dpp_rol1(fr == 0 ? dv : xv), ng = dpp_rol1(fr == 0 ? dg : xg);
;                         const float yv = wv0[i] * pv + wv1[i] * xv + wv2[i] * nv + bv[i];
;                         const float yg = wg0[i] * pg + wg1[i] * xg + wg2[i] * ng + bg[i];
;                         r[i] = yg * sigmoidf_(yg) * yv;
;                     }
;                     st_bf4(ACT + (size_t)(u.pm * BM + ai * HALF + wr * 64 + m * 16 + fr) * FF + cv, r);
	v_pk_fma_f32 v[118:119], v[126:127], v[158:159], v[118:119]
	s_nop 0
	v_mov_b32_dpp v209, v171 row_ror:15 row_mask:0xf bank_mask:0xf
	v_add_u32_e32 v171, s17, v198
	v_mad_i64_i32 v[112:113], s[28:29], v171, s46, v[184:185]
	v_add_f32_e32 v171, 1.0, v212
	v_mul_f32_e32 v212, 0xbfb8aa3b, v157
	v_exp_f32_e32 v213, v212
	v_rcp_f32_e32 v212, v171
	v_pk_fma_f32 v[114:115], v[138:139], v[208:209], v[114:115]
	v_pk_add_f32 v[118:119], v[130:131], v[118:119]
	v_add_f32_e32 v171, 1.0, v213
	v_rcp_f32_e32 v213, v171
	v_pk_add_f32 v[114:115], v[142:143], v[114:115]
	v_lshl_add_u64 v[112:113], v[112:113], 0, v[186:187]
	v_pk_mul_f32 v[154:155], v[156:157], v[212:213]
	s_nop 0
	v_pk_mul_f32 v[116:117], v[116:117], v[154:155]
	v_mul_f32_e32 v154, 0xbfb8aa3b, v114
	v_exp_f32_e32 v154, v154
	v_mul_f32_e32 v155, 0xbfb8aa3b, v115
	v_exp_f32_e32 v155, v155
	v_cvt_pk_bf16_f32 v116, v116, v117
	v_add_f32_e32 v117, 1.0, v154
	v_rcp_f32_e32 v154, v117
	v_add_f32_e32 v117, 1.0, v155
	v_rcp_f32_e32 v155, v117
	v_cndmask_b32_e64 v156, v99, 0, s[6:7]
	v_pk_mul_f32 v[114:115], v[114:115], v[154:155]
	s_nop 0
	v_pk_mul_f32 v[114:115], v[118:119], v[114:115]
	v_cndmask_b32_e64 v118, v97, 0, s[6:7]
	v_cvt_pk_bf16_f32 v117, v114, v115
	v_cndmask_b32_e64 v114, v100, v108, s[4:5]
	global_store_dwordx2 v[112:113], v[116:117], off
	s_nop 0
	v_mov_b32_dpp v108, v114 row_ror:1 row_mask:0xf bank_mask:0xf
	v_cndmask_b32_e64 v114, v96, v104, s[4:5]
	v_cndmask_b32_e64 v117, v101, 0, s[6:7]
	s_nop 0
	v_mov_b32_dpp v104, v114 row_ror:1 row_mask:0xf bank_mask:0xf
	v_mov_b32_dpp v114, v100 row_shl:1 row_mask:0xf bank_mask:0xf bound_ctrl:1
	s_nop 0
	v_mov_b32_dpp v116, v96 row_shl:1 row_mask:0xf bank_mask:0xf bound_ctrl:1
	v_cndmask_b32_e64 v115, v101, v109, s[4:5]
	v_pk_mul_f32 v[100:101], v[100:101], v[144:145]
	s_nop 0
	v_mov_b32_dpp v109, v115 row_ror:1 row_mask:0xf bank_mask:0xf
	v_cndmask_b32_e64 v115, v97, v105, s[4:5]
	v_pk_mul_f32 v[96:97], v[96:97], v[148:149]
	v_pk_fma_f32 v[100:101], v[120:121], v[108:109], v[100:101]
	v_mov_b32_dpp v105, v115 row_ror:1 row_mask:0xf bank_mask:0xf
	v_pk_fma_f32 v[96:97], v[132:133], v[104:105], v[96:97]
	v_mov_b32_dpp v115, v117 row_ror:15 row_mask:0xf bank_mask:0xf
	v_pk_fma_f32 v[100:101], v[124:125], v[114:115], v[100:101]
	v_mov_b32_dpp v117, v118 row_ror:15 row_mask:0xf bank_mask:0xf
	v_pk_fma_f32 v[96:97], v[136:137], v[116:117], v[96:97]
	v_cndmask_b32_e64 v118, v102, v110, s[4:5]
	v_pk_add_f32 v[104:105], v[140:141], v[96:97]
	s_nop 0
	v_mul_f32_e32 v96, 0xbfb8aa3b, v104
	v_mul_f32_e32 v117, 0xbfb8aa3b, v105
	v_mov_b32_dpp v110, v118 row_ror:1 row_mask:0xf bank_mask:0xf
	v_cndmask_b32_e64 v118, v98, v106, s[4:5]
	v_exp_f32_e32 v116, v96
	v_exp_f32_e32 v117, v117
	v_mov_b32_dpp v106, v118 row_ror:1 row_mask:0xf bank_mask:0xf
	v_add_f32_e32 v116, 1.0, v116
	v_add_f32_e32 v117, 1.0, v117
	v_mov_b32_dpp v118, v102 row_shl:1 row_mask:0xf bank_mask:0xf bound_ctrl:1
	v_rcp_f32_e32 v116, v116
	v_rcp_f32_e32 v117, v117
	v_mov_b32_dpp v154, v98 row_shl:1 row_mask:0xf bank_mask:0xf bound_ctrl:1
	v_cndmask_b32_e64 v119, v103, v111, s[4:5]
	v_pk_add_f32 v[100:101], v[128:129], v[100:101]
	v_pk_mul_f32 v[104:105], v[104:105], v[116:117]
	v_mov_b32_dpp v111, v119 row_ror:1 row_mask:0xf bank_mask:0xf
	v_cndmask_b32_e64 v119, v99, v107, s[4:5]
	v_pk_mul_f32 v[98:99], v[98:99], v[150:151]
	v_pk_mul_f32 v[100:101], v[100:101], v[104:105]
	v_mov_b32_dpp v107, v119 row_ror:1 row_mask:0xf bank_mask:0xf
	v_pk_fma_f32 v[98:99], v[134:135], v[106:107], v[98:99]
	v_cvt_pk_bf16_f32 v100, v100, v101
	v_mov_b32_dpp v119, v103 row_shl:1 row_mask:0xf bank_mask:0xf bound_ctrl:1
	v_pk_mul_f32 v[102:103], v[102:103], v[146:147]
	v_cndmask_b32_e64 v106, v89, v81, s[6:7]
	v_mov_b32_dpp v155, v156 row_ror:15 row_mask:0xf bank_mask:0xf
	v_pk_fma_f32 v[98:99], v[138:139], v[154:155], v[98:99]
	v_pk_fma_f32 v[102:103], v[122:123], v[110:111], v[102:103]
	v_pk_add_f32 v[98:99], v[142:143], v[98:99]
	v_pk_fma_f32 v[102:103], v[126:127], v[118:119], v[102:103]
	v_mul_f32_e32 v104, 0xbfb8aa3b, v98
	v_exp_f32_e32 v104, v104
	v_mul_f32_e32 v105, 0xbfb8aa3b, v99
	v_exp_f32_e32 v105, v105
	v_add_u32_e32 v156, s17, v199
	v_add_f32_e32 v101, 1.0, v104
	v_rcp_f32_e32 v104, v101
	v_add_f32_e32 v101, 1.0, v105
	v_rcp_f32_e32 v105, v101
	v_pk_add_f32 v[102:103], v[130:131], v[102:103]
	v_mad_i64_i32 v[96:97], s[28:29], v156, s46, v[184:185]
	v_pk_mul_f32 v[98:99], v[98:99], v[104:105]
	v_lshl_add_u64 v[96:97], v[96:97], 0, v[186:187]
	v_pk_mul_f32 v[98:99], v[102:103], v[98:99]
	s_nop 0
	v_cvt_pk_bf16_f32 v101, v98, v99
	global_store_dwordx2 v[96:97], v[100:101], off
	v_mov_b32_dpp v100, v92 row_shr:1 row_mask:0xf bank_mask:0xf bound_ctrl:1
	v_mov_b32_dpp v98, v88 row_shr:1 row_mask:0xf bank_mask:0xf bound_ctrl:1
	v_cndmask_b32_e64 v99, v92, v84, s[6:7]
	v_cndmask_b32_e64 v105, v93, v85, s[6:7]
	s_nop 0
	v_mov_b32_dpp v102, v99 row_ror:15 row_mask:0xf bank_mask:0xf
	v_cndmask_b32_e64 v99, v88, v80, s[6:7]
	s_nop 1
	v_mov_b32_dpp v104, v99 row_ror:15 row_mask:0xf bank_mask:0xf
	v_cndmask_b32_e64 v115, v95, v87, s[6:7]
	v_mov_b32_dpp v101, v93 row_shr:1 row_mask:0xf bank_mask:0xf bound_ctrl:1
	v_cndmask_b32_e64 v116, v91, v83, s[6:7]
	v_add_u32_e32 v118, s17, v200
	v_mov_b32_dpp v99, v89 row_shr:1 row_mask:0xf bank_mask:0xf bound_ctrl:1
	v_pk_mul_f32 v[156:157], v[92:93], v[144:145]
	v_pk_mul_f32 v[154:155], v[94:95], v[146:147]
	v_mov_b32_dpp v103, v105 row_ror:15 row_mask:0xf bank_mask:0xf
	v_pk_fma_f32 v[100:101], v[120:121], v[100:101], v[156:157]
	s_nop 0
	v_mov_b32_dpp v105, v106 row_ror:15 row_mask:0xf bank_mask:0xf
	v_pk_fma_f32 v[100:101], v[124:125], v[102:103], v[100:101]
; __device__ __forceinline__ void st_bf4(bf16_t* p, f32x4 v) { u32x2 w; w.x = pk2(v[0], v[1]); w.y = pk2(v[2], v[3]); *(u32x2*)p = w; }
; __device__ __forceinline__ float sigmoidf_(float x) { return __builtin_amdgcn_rcpf(1.f + __expf(-x)); }
; __device__ __forceinline__ float dpp_ror1(float v) { return __int_as_float(__builtin_amdgcn_update_dpp(0, __float_as_int(v), 0x121, 0xf, 0xf, false)); }
; __device__ __forceinline__ float dpp_rol1(float v) { return __int_as_float(__builtin_amdgcn_update_dpp(0, __float_as_int(v), 0x12F, 0xf, 0xf, false)); }
;     __device__ __forceinline__ void tile(const f32x4 (&acc)[2][2][4][2], const Unit& u, int wr, int wc, int fr, int fq) const {
;     ...
;                         const float xv = acc[ai][0][m][n][i], xg = acc[ai][1][m][n][i];
;                         const float uv = m > 0 ? acc[ai][0][m > 0 ? m - 1 : 0][n][i] : 0.f, ug = m > 0 ? acc[ai][1][m > 0 ? m - 1 : 0][n][i] : 0.f;
;                         const float dv = m < 3 ? acc[ai][0][m < 3 ? m + 1 : 3][n][i] : 0.f, dg = m < 3 ? acc[ai][1][m < 3 ? m + 1 : 3][n][i] : 0.f;
;                         const float pv = dpp_ror1(fr == 15 ? uv : xv), pg = dpp_ror1(fr == 15 ? ug : xg);
;                         const float nv = dpp_rol1(fr == 0 ? dv : xv), ng = dpp_rol1(fr == 0 ? dg : xg);
;                         const float yv = wv0[i] * pv + wv1[i] * xv + wv2[i] * nv + bv[i];
;                         const float yg = wg0[i] * pg + wg1[i] * xg + wg2[i] * ng + bg[i];
;                         r[i] = yg * sigmoidf_(yg) * yv;
;                     }
;                     st_bf4(ACT + (size_t)(u.pm * BM + ai * HALF + wr * 64 + m * 16 + fr) * FF + cv, r);
	s_nop 0
	v_mov_b32_dpp v106, v94 row_shr:1 row_mask:0xf bank_mask:0xf bound_ctrl:1
	v_pk_add_f32 v[100:101], v[128:129], v[100:101]
	s_nop 0
	v_mov_b32_dpp v108, v90 row_shr:1 row_mask:0xf bank_mask:0xf bound_ctrl:1
	v_cndmask_b32_e64 v107, v94, v86, s[6:7]
	s_nop 1
	v_mov_b32_dpp v110, v107 row_ror:15 row_mask:0xf bank_mask:0xf
	v_cndmask_b32_e64 v107, v90, v82, s[6:7]
	s_nop 1
	v_mov_b32_dpp v114, v107 row_ror:15 row_mask:0xf bank_mask:0xf
	s_nop 1
	v_mov_b32_dpp v107, v95 row_shr:1 row_mask:0xf bank_mask:0xf bound_ctrl:1
	v_pk_fma_f32 v[106:107], v[122:123], v[106:107], v[154:155]
	s_nop 0
	v_mov_b32_dpp v109, v91 row_shr:1 row_mask:0xf bank_mask:0xf bound_ctrl:1
	s_nop 1
	v_mov_b32_dpp v111, v115 row_ror:15 row_mask:0xf bank_mask:0xf
	v_pk_fma_f32 v[106:107], v[126:127], v[110:111], v[106:107]
	v_add_u32_e32 v110, s17, v201
	v_mov_b32_dpp v115, v116 row_ror:15 row_mask:0xf bank_mask:0xf
	v_pk_mul_f32 v[116:117], v[88:89], v[148:149]
	v_pk_add_f32 v[106:107], v[130:131], v[106:107]
	v_pk_fma_f32 v[98:99], v[132:133], v[98:99], v[116:117]
	v_pk_mul_f32 v[116:117], v[90:91], v[150:151]
	v_pk_fma_f32 v[98:99], v[136:137], v[104:105], v[98:99]
	s_nop 0
	v_pk_add_f32 v[104:105], v[140:141], v[98:99]
	s_nop 0
	v_mul_f32_e32 v98, 0xbfb8aa3b, v104
	v_exp_f32_e32 v119, v98
	v_mad_i64_i32 v[98:99], s[28:29], v118, s46, v[184:185]
	v_lshl_add_u64 v[98:99], v[98:99], 0, v[186:187]
	v_add_f32_e32 v118, 1.0, v119
	v_mul_f32_e32 v119, 0xbfb8aa3b, v105
	v_exp_f32_e32 v119, v119
	v_rcp_f32_e32 v118, v118
	v_add_f32_e32 v119, 1.0, v119
	v_rcp_f32_e32 v119, v119
	s_nop 0
	v_pk_mul_f32 v[102:103], v[104:105], v[118:119]
	s_nop 0
	v_pk_mul_f32 v[100:101], v[100:101], v[102:103]
	v_pk_fma_f32 v[102:103], v[134:135], v[108:109], v[116:117]
	v_cvt_pk_bf16_f32 v100, v100, v101
	v_pk_fma_f32 v[102:103], v[138:139], v[114:115], v[102:103]
	v_cndmask_b32_e64 v108, v83, v75, s[6:7]
	v_pk_add_f32 v[102:103], v[142:143], v[102:103]
	v_pk_mul_f32 v[116:117], v[84:85], v[144:145]
	v_mul_f32_e32 v104, 0xbfb8aa3b, v102
	v_exp_f32_e32 v104, v104
	v_mul_f32_e32 v105, 0xbfb8aa3b, v103
	v_exp_f32_e32 v105, v105
	v_pk_mul_f32 v[114:115], v[86:87], v[146:147]
	v_add_f32_e32 v101, 1.0, v104
	v_rcp_f32_e32 v104, v101
	v_add_f32_e32 v101, 1.0, v105
	v_rcp_f32_e32 v105, v101
	s_nop 0
	v_pk_mul_f32 v[102:103], v[102:103], v[104:105]
	s_nop 0
	v_pk_mul_f32 v[102:103], v[106:107], v[102:103]
	v_cndmask_b32_e64 v104, v81, v73, s[6:7]
	v_cvt_pk_bf16_f32 v101, v102, v103
	global_store_dwordx2 v[98:99], v[100:101], off
	v_cndmask_b32_e64 v100, v84, v92, s[4:5]
	v_cndmask_b32_e64 v101, v80, v72, s[6:7]
	s_nop 0
	v_mov_b32_dpp v92, v100 row_ror:1 row_mask:0xf bank_mask:0xf
	v_cndmask_b32_e64 v100, v80, v88, s[4:5]
	v_cndmask_b32_e64 v105, v86, v78, s[6:7]
	s_nop 0
	v_mov_b32_dpp v88, v100 row_ror:1 row_mask:0xf bank_mask:0xf
	v_cndmask_b32_e64 v100, v84, v76, s[6:7]
	v_cndmask_b32_e64 v107, v87, v79, s[6:7]
	s_nop 0
	v_mov_b32_dpp v102, v100 row_ror:15 row_mask:0xf bank_mask:0xf
	s_nop 1
	v_mov_b32_dpp v100, v101 row_ror:15 row_mask:0xf bank_mask:0xf
	v_cndmask_b32_e64 v101, v85, v93, s[4:5]
	s_nop 1
	v_mov_b32_dpp v93, v101 row_ror:1 row_mask:0xf bank_mask:0xf
	v_cndmask_b32_e64 v101, v81, v89, s[4:5]
	v_pk_fma_f32 v[92:93], v[120:121], v[92:93], v[116:117]
	v_cndmask_b32_e64 v116, v57, v49, s[6:7]
	v_mov_b32_dpp v89, v101 row_ror:1 row_mask:0xf bank_mask:0xf
	v_cndmask_b32_e64 v101, v85, v77, s[6:7]
	s_nop 0
	s_nop 0
	v_mov_b32_dpp v103, v101 row_ror:15 row_mask:0xf bank_mask:0xf
	v_pk_fma_f32 v[92:93], v[124:125], v[102:103], v[92:93]
	v_cndmask_b32_e64 v102, v75, v67, s[6:7]
	v_mov_b32_dpp v101, v104 row_ror:15 row_mask:0xf bank_mask:0xf
	v_cndmask_b32_e64 v104, v86, v94, s[4:5]
	v_pk_add_f32 v[92:93], v[128:129], v[92:93]
	s_nop 0
	v_mov_b32_dpp v94, v104 row_ror:1 row_mask:0xf bank_mask:0xf
	v_cndmask_b32_e64 v104, v82, v90, s[4:5]
	s_nop 1
	v_mov_b32_dpp v90, v104 row_ror:1 row_mask:0xf bank_mask:0xf
	s_nop 1
	v_mov_b32_dpp v104, v105 row_ror:15 row_mask:0xf bank_mask:0xf
	v_cndmask_b32_e64 v105, v82, v74, s[6:7]
	s_nop 1
	v_mov_b32_dpp v106, v105 row_ror:15 row_mask:0xf bank_mask:0xf
	v_cndmask_b32_e64 v105, v87, v95, s[4:5]
	s_nop 1
	v_mov_b32_dpp v95, v105 row_ror:1 row_mask:0xf bank_mask:0xf
	v_cndmask_b32_e64 v105, v83, v91, s[4:5]
	v_pk_fma_f32 v[94:95], v[122:123], v[94:95], v[114:115]
	s_nop 0
	v_mov_b32_dpp v91, v105 row_ror:1 row_mask:0xf bank_mask:0xf
	v_cndmask_b32_e64 v115, v61, v53, s[6:7]
	s_nop 0
	v_mov_b32_dpp v105, v107 row_ror:15 row_mask:0xf bank_mask:0xf
	v_pk_fma_f32 v[94:95], v[126:127], v[104:105], v[94:95]
	v_add_u32_e32 v104, s17, v202
	v_mov_b32_dpp v107, v108 row_ror:15 row_mask:0xf bank_mask:0xf
	v_pk_mul_f32 v[108:109], v[80:81], v[148:149]
	v_pk_add_f32 v[94:95], v[130:131], v[94:95]
	v_pk_fma_f32 v[88:89], v[132:133], v[88:89], v[108:109]
	v_pk_mul_f32 v[108:109], v[82:83], v[150:151]
	v_pk_fma_f32 v[88:89], v[136:137], v[100:101], v[88:89]
	v_pk_fma_f32 v[90:91], v[134:135], v[90:91], v[108:109]
	v_pk_add_f32 v[88:89], v[140:141], v[88:89]
	v_pk_fma_f32 v[90:91], v[138:139], v[106:107], v[90:91]
	v_mul_f32_e32 v100, 0xbfb8aa3b, v88
	v_exp_f32_e32 v111, v100
	v_mad_i64_i32 v[100:101], s[28:29], v110, s46, v[184:185]
	v_pk_add_f32 v[90:91], v[142:143], v[90:91]
	v_add_f32_e32 v110, 1.0, v111
	v_mul_f32_e32 v111, 0xbfb8aa3b, v89
	v_exp_f32_e32 v111, v111
	v_rcp_f32_e32 v110, v110
	v_lshl_add_u64 v[100:101], v[100:101], 0, v[186:187]
	v_pk_mul_f32 v[108:109], v[76:77], v[144:145]
	v_add_f32_e32 v111, 1.0, v111
	v_rcp_f32_e32 v111, v111
	v_pk_mul_f32 v[106:107], v[78:79], v[146:147]
	v_pk_mul_f32 v[88:89], v[88:89], v[110:111]
	s_nop 0
; __device__ __forceinline__ void st_bf4(bf16_t* p, f32x4 v) { u32x2 w; w.x = pk2(v[0], v[1]); w.y = pk2(v[2], v[3]); *(u32x2*)p = w; }
; __device__ __forceinline__ float sigmoidf_(float x) { return __builtin_amdgcn_rcpf(1.f + __expf(-x)); }
; __device__ __forceinline__ float dpp_ror1(float v) { return __int_as_float(__builtin_amdgcn_update_dpp(0, __float_as_int(v), 0x121, 0xf, 0xf, false)); }
; __device__ __forceinline__ float dpp_rol1(float v) { return __int_as_float(__builtin_amdgcn_update_dpp(0, __float_as_int(v), 0x12F, 0xf, 0xf, false)); }
;     __device__ __forceinline__ void tile(const f32x4 (&acc)[2][2][4][2], const Unit& u, int wr, int wc, int fr, int fq) const {
;     ...
;         for (int n = 0; n < 2; ++n) {
;             const int cv = 128 * u.pn + 32 * wc + 16 * n + 4 * fq, cg = FF + cv;
;             const f32x4 wv0 = *(const f32x4*)(cw + cv), wv1 = *(const f32x4*)(cw + F2 + cv), wv2 = *(const f32x4*)(cw + 2 * F2 + cv), bv = *(const f32x4*)(cb + cv);
;             const f32x4 wg0 = *(const f32x4*)(cw + cg), wg1 = *(const f32x4*)(cw + F2 + cg), wg2 = *(const f32x4*)(cw + 2 * F2 + cg), bg = *(const f32x4*)(cb + cg);
; #pragma unroll
;             for (int ai = 0; ai < 2; ++ai)
; #pragma unroll
;                 for (int m = 0; m < 4; ++m) {
;                     f32x4 r;
; #pragma unroll
;                     for (int i = 0; i < 4; ++i) {
;                         const float xv = acc[ai][0][m][n][i], xg = acc[ai][1][m][n][i];
;                         const float uv = m > 0 ? acc[ai][0][m > 0 ? m - 1 : 0][n][i] : 0.f, ug = m > 0 ? acc[ai][1][m > 0 ? m - 1 : 0][n][i] : 0.f;
;                         const float dv = m < 3 ? acc[ai][0][m < 3 ? m + 1 : 3][n][i] : 0.f, dg = m < 3 ? acc[ai][1][m < 3 ? m + 1 : 3][n][i] : 0.f;
;                         const float pv = dpp_ror1(fr == 15 ? uv : xv), pg = dpp_ror1(fr == 15 ? ug : xg);
;                         const float nv = dpp_rol1(fr == 0 ? dv : xv), ng = dpp_rol1(fr == 0 ? dg : xg);
;                         const float yv = wv0[i] * pv + wv1[i] * xv + wv2[i] * nv + bv[i];
;                         const float yg = wg0[i] * pg + wg1[i] * xg + wg2[i] * ng + bg[i];
;                         r[i] = yg * sigmoidf_(yg) * yv;
;                     }
;                     st_bf4(ACT + (size_t)(u.pm * BM + ai * HALF + wr * 64 + m * 16 + fr) * FF + cv, r);
;                 }
	v_pk_mul_f32 v[88:89], v[92:93], v[88:89]
	v_mul_f32_e32 v92, 0xbfb8aa3b, v90
	v_exp_f32_e32 v92, v92
	v_mul_f32_e32 v93, 0xbfb8aa3b, v91
	v_exp_f32_e32 v93, v93
	v_cvt_pk_bf16_f32 v88, v88, v89
	v_add_f32_e32 v89, 1.0, v92
	v_rcp_f32_e32 v92, v89
	v_add_f32_e32 v89, 1.0, v93
	v_rcp_f32_e32 v93, v89
	s_nop 0
	v_pk_mul_f32 v[90:91], v[90:91], v[92:93]
	s_nop 0
	v_pk_mul_f32 v[90:91], v[94:95], v[90:91]
	v_cndmask_b32_e64 v92, v73, v65, s[6:7]
	v_cvt_pk_bf16_f32 v89, v90, v91
	global_store_dwordx2 v[100:101], v[88:89], off
	v_cndmask_b32_e64 v88, v76, v84, s[4:5]
	v_cndmask_b32_e64 v89, v76, v68, s[6:7]
	s_nop 0
	v_mov_b32_dpp v84, v88 row_ror:1 row_mask:0xf bank_mask:0xf
	v_cndmask_b32_e64 v88, v72, v80, s[4:5]
	v_cndmask_b32_e64 v91, v77, v69, s[6:7]
	v_cndmask_b32_e64 v93, v78, v70, s[6:7]
	v_mov_b32_dpp v80, v88 row_ror:1 row_mask:0xf bank_mask:0xf
	v_cndmask_b32_e64 v95, v79, v71, s[6:7]
	v_mov_b32_dpp v88, v89 row_ror:15 row_mask:0xf bank_mask:0xf
	v_cndmask_b32_e64 v89, v72, v64, s[6:7]
	s_nop 1
	v_mov_b32_dpp v90, v89 row_ror:15 row_mask:0xf bank_mask:0xf
	v_cndmask_b32_e64 v89, v77, v85, s[4:5]
	s_nop 1
	v_mov_b32_dpp v85, v89 row_ror:1 row_mask:0xf bank_mask:0xf
	v_cndmask_b32_e64 v89, v73, v81, s[4:5]
	v_pk_fma_f32 v[84:85], v[120:121], v[84:85], v[108:109]
	s_nop 0
	v_mov_b32_dpp v81, v89 row_ror:1 row_mask:0xf bank_mask:0xf
	s_nop 0
	v_mov_b32_dpp v89, v91 row_ror:15 row_mask:0xf bank_mask:0xf
	v_pk_fma_f32 v[84:85], v[124:125], v[88:89], v[84:85]
	v_cndmask_b32_e64 v88, v67, 0, s[6:7]
	v_mov_b32_dpp v91, v92 row_ror:15 row_mask:0xf bank_mask:0xf
	v_cndmask_b32_e64 v92, v78, v86, s[4:5]
	v_pk_add_f32 v[84:85], v[128:129], v[84:85]
	s_nop 0
	v_mov_b32_dpp v86, v92 row_ror:1 row_mask:0xf bank_mask:0xf
	v_cndmask_b32_e64 v92, v74, v82, s[4:5]
	s_nop 1
	v_mov_b32_dpp v82, v92 row_ror:1 row_mask:0xf bank_mask:0xf
	s_nop 1
	v_mov_b32_dpp v92, v93 row_ror:15 row_mask:0xf bank_mask:0xf
	v_cndmask_b32_e64 v93, v74, v66, s[6:7]
	s_nop 1
	v_mov_b32_dpp v94, v93 row_ror:15 row_mask:0xf bank_mask:0xf
	v_cndmask_b32_e64 v93, v79, v87, s[4:5]
	s_nop 1
	v_mov_b32_dpp v87, v93 row_ror:1 row_mask:0xf bank_mask:0xf
	v_cndmask_b32_e64 v93, v75, v83, s[4:5]
	v_pk_fma_f32 v[86:87], v[122:123], v[86:87], v[106:107]
	s_nop 0
	v_mov_b32_dpp v83, v93 row_ror:1 row_mask:0xf bank_mask:0xf
	s_nop 0
	v_mov_b32_dpp v93, v95 row_ror:15 row_mask:0xf bank_mask:0xf
	v_pk_fma_f32 v[86:87], v[126:127], v[92:93], v[86:87]
	v_mov_b32_dpp v106, v60 row_shr:1 row_mask:0xf bank_mask:0xf bound_ctrl:1
	v_mov_b32_dpp v95, v102 row_ror:15 row_mask:0xf bank_mask:0xf
	v_pk_mul_f32 v[102:103], v[72:73], v[148:149]
	v_pk_add_f32 v[86:87], v[130:131], v[86:87]
	v_pk_fma_f32 v[80:81], v[132:133], v[80:81], v[102:103]
	s_nop 0
	v_pk_fma_f32 v[80:81], v[136:137], v[90:91], v[80:81]
	s_nop 0
	v_pk_add_f32 v[80:81], v[140:141], v[80:81]
	v_mov_b32_dpp v108, v56 row_shr:1 row_mask:0xf bank_mask:0xf bound_ctrl:1
	v_mul_f32_e32 v90, 0xbfb8aa3b, v80
	v_exp_f32_e32 v105, v90
	v_mad_i64_i32 v[90:91], s[28:29], v104, s46, v[184:185]
	v_lshl_add_u64 v[102:103], v[90:91], 0, v[186:187]
	v_add_f32_e32 v104, 1.0, v105
	v_mul_f32_e32 v105, 0xbfb8aa3b, v81
	v_exp_f32_e32 v105, v105
	v_rcp_f32_e32 v104, v104
	v_pk_mul_f32 v[90:91], v[74:75], v[150:151]
	v_cndmask_b32_e64 v107, v60, v52, s[6:7]
	v_add_f32_e32 v105, 1.0, v105
	v_rcp_f32_e32 v105, v105
	v_pk_fma_f32 v[82:83], v[134:135], v[82:83], v[90:91]
	v_mov_b32_dpp v110, v107 row_ror:15 row_mask:0xf bank_mask:0xf
	v_pk_fma_f32 v[82:83], v[138:139], v[94:95], v[82:83]
	v_pk_mul_f32 v[80:81], v[80:81], v[104:105]
	v_pk_add_f32 v[82:83], v[142:143], v[82:83]
	v_pk_mul_f32 v[80:81], v[84:85], v[80:81]
	v_mul_f32_e32 v84, 0xbfb8aa3b, v82
	v_exp_f32_e32 v84, v84
	v_mul_f32_e32 v85, 0xbfb8aa3b, v83
	v_exp_f32_e32 v85, v85
	v_cvt_pk_bf16_f32 v80, v80, v81
	v_add_f32_e32 v81, 1.0, v84
	v_rcp_f32_e32 v84, v81
	v_add_f32_e32 v81, 1.0, v85
	v_rcp_f32_e32 v85, v81
	v_cndmask_b32_e64 v107, v56, v48, s[6:7]
	v_pk_mul_f32 v[82:83], v[82:83], v[84:85]
	s_nop 0
	v_pk_mul_f32 v[82:83], v[86:87], v[82:83]
	v_cndmask_b32_e64 v84, v65, 0, s[6:7]
	v_cvt_pk_bf16_f32 v81, v82, v83
	global_store_dwordx2 v[102:103], v[80:81], off
	v_cndmask_b32_e64 v80, v68, v76, s[4:5]
	s_nop 1
	v_mov_b32_dpp v76, v80 row_ror:1 row_mask:0xf bank_mask:0xf
	v_cndmask_b32_e64 v80, v64, v72, s[4:5]
	v_cndmask_b32_e64 v83, v69, 0, s[6:7]
	s_nop 0
	v_mov_b32_dpp v72, v80 row_ror:1 row_mask:0xf bank_mask:0xf
	v_cndmask_b32_e64 v87, v71, 0, s[6:7]
	v_mov_b32_dpp v80, v68 row_shl:1 row_mask:0xf bank_mask:0xf bound_ctrl:1
	v_mov_b32_dpp v114, v107 row_ror:15 row_mask:0xf bank_mask:0xf
	v_mov_b32_dpp v82, v64 row_shl:1 row_mask:0xf bank_mask:0xf bound_ctrl:1
	v_cndmask_b32_e64 v81, v69, v77, s[4:5]
	v_pk_mul_f32 v[68:69], v[68:69], v[144:145]
	v_mov_b32_dpp v107, v61 row_shr:1 row_mask:0xf bank_mask:0xf bound_ctrl:1
	v_mov_b32_dpp v77, v81 row_ror:1 row_mask:0xf bank_mask:0xf
	v_cndmask_b32_e64 v81, v65, v73, s[4:5]
	v_pk_mul_f32 v[64:65], v[64:65], v[148:149]
	v_pk_fma_f32 v[68:69], v[120:121], v[76:77], v[68:69]
	v_mov_b32_dpp v73, v81 row_ror:1 row_mask:0xf bank_mask:0xf
	v_pk_fma_f32 v[64:65], v[132:133], v[72:73], v[64:65]
	v_mov_b32_dpp v81, v83 row_ror:15 row_mask:0xf bank_mask:0xf
	v_pk_fma_f32 v[68:69], v[124:125], v[80:81], v[68:69]
	v_mov_b32_dpp v109, v57 row_shr:1 row_mask:0xf bank_mask:0xf bound_ctrl:1
	v_mov_b32_dpp v83, v84 row_ror:15 row_mask:0xf bank_mask:0xf
	v_cndmask_b32_e64 v84, v70, v78, s[4:5]
	v_pk_fma_f32 v[64:65], v[136:137], v[82:83], v[64:65]
	v_pk_add_f32 v[68:69], v[128:129], v[68:69]
	v_mov_b32_dpp v78, v84 row_ror:1 row_mask:0xf bank_mask:0xf
; __device__ __forceinline__ void st_bf4(bf16_t* p, f32x4 v) { u32x2 w; w.x = pk2(v[0], v[1]); w.y = pk2(v[2], v[3]); *(u32x2*)p = w; }
; __device__ __forceinline__ float sigmoidf_(float x) { return __builtin_amdgcn_rcpf(1.f + __expf(-x)); }
; __device__ __forceinline__ float dpp_ror1(float v) { return __int_as_float(__builtin_amdgcn_update_dpp(0, __float_as_int(v), 0x121, 0xf, 0xf, false)); }
; __device__ __forceinline__ float dpp_rol1(float v) { return __int_as_float(__builtin_amdgcn_update_dpp(0, __float_as_int(v), 0x12F, 0xf, 0xf, false)); }
;     __device__ __forceinline__ void tile(const f32x4 (&acc)[2][2][4][2], const Unit& u, int wr, int wc, int fr, int fq) const {
;     ...
;         for (int n = 0; n < 2; ++n) {
;             const int cv = 128 * u.pn + 32 * wc + 16 * n + 4 * fq, cg = FF + cv;
;             const f32x4 wv0 = *(const f32x4*)(cw + cv), wv1 = *(const f32x4*)(cw + F2 + cv), wv2 = *(const f32x4*)(cw + 2 * F2 + cv), bv = *(const f32x4*)(cb + cv);
;             const f32x4 wg0 = *(const f32x4*)(cw + cg), wg1 = *(const f32x4*)(cw + F2 + cg), wg2 = *(const f32x4*)(cw + 2 * F2 + cg), bg = *(const f32x4*)(cb + cg);
; #pragma unroll
;             for (int ai = 0; ai < 2; ++ai)
; #pragma unroll
;                 for (int m = 0; m < 4; ++m) {
;                     f32x4 r;
; #pragma unroll
;                     for (int i = 0; i < 4; ++i) {
;                         const float xv = acc[ai][0][m][n][i], xg = acc[ai][1][m][n][i];
;                         const float uv = m > 0 ? acc[ai][0][m > 0 ? m - 1 : 0][n][i] : 0.f, ug = m > 0 ? acc[ai][1][m > 0 ? m - 1 : 0][n][i] : 0.f;
;                         const float dv = m < 3 ? acc[ai][0][m < 3 ? m + 1 : 3][n][i] : 0.f, dg = m < 3 ? acc[ai][1][m < 3 ? m + 1 : 3][n][i] : 0.f;
;                         const float pv = dpp_ror1(fr == 15 ? uv : xv), pg = dpp_ror1(fr == 15 ? ug : xg);
;                         const float nv = dpp_rol1(fr == 0 ? dv : xv), ng = dpp_rol1(fr == 0 ? dg : xg);
;                         const float yv = wv0[i] * pv + wv1[i] * xv + wv2[i] * nv + bv[i];
;                         const float yg = wg0[i] * pg + wg1[i] * xg + wg2[i] * ng + bg[i];
;                         r[i] = yg * sigmoidf_(yg) * yv;
;                     }
;                     st_bf4(ACT + (size_t)(u.pm * BM + ai * HALF + wr * 64 + m * 16 + fr) * FF + cv, r);
;                 }
	v_cndmask_b32_e64 v84, v66, v74, s[4:5]
	v_pk_add_f32 v[64:65], v[140:141], v[64:65]
	s_nop 0
	v_mov_b32_dpp v74, v84 row_ror:1 row_mask:0xf bank_mask:0xf
	v_mul_f32_e32 v72, 0xbfb8aa3b, v64
	v_exp_f32_e32 v82, v72
	v_mov_b32_dpp v84, v70 row_shl:1 row_mask:0xf bank_mask:0xf bound_ctrl:1
	v_mov_b32_dpp v111, v115 row_ror:15 row_mask:0xf bank_mask:0xf
	v_mov_b32_dpp v86, v66 row_shl:1 row_mask:0xf bank_mask:0xf bound_ctrl:1
	v_cndmask_b32_e64 v85, v71, v79, s[4:5]
	v_pk_mul_f32 v[70:71], v[70:71], v[146:147]
	v_mov_b32_dpp v115, v116 row_ror:15 row_mask:0xf bank_mask:0xf
	v_mov_b32_dpp v79, v85 row_ror:1 row_mask:0xf bank_mask:0xf
	v_cndmask_b32_e64 v85, v67, v75, s[4:5]
	v_pk_mul_f32 v[66:67], v[66:67], v[150:151]
	v_pk_fma_f32 v[70:71], v[122:123], v[78:79], v[70:71]
	v_mov_b32_dpp v75, v85 row_ror:1 row_mask:0xf bank_mask:0xf
	v_pk_fma_f32 v[66:67], v[134:135], v[74:75], v[66:67]
	v_mov_b32_dpp v85, v87 row_ror:15 row_mask:0xf bank_mask:0xf
	v_pk_fma_f32 v[70:71], v[126:127], v[84:85], v[70:71]
	v_mov_b32_dpp v116, v62 row_shr:1 row_mask:0xf bank_mask:0xf bound_ctrl:1
	v_mov_b32_dpp v87, v88 row_ror:15 row_mask:0xf bank_mask:0xf
	v_add_u32_e32 v88, s17, v203
	v_mad_i64_i32 v[72:73], s[28:29], v88, s46, v[184:185]
	v_lshl_add_u64 v[104:105], v[72:73], 0, v[186:187]
	v_mul_f32_e32 v73, 0xbfb8aa3b, v65
	v_exp_f32_e32 v73, v73
	v_add_f32_e32 v72, 1.0, v82
	v_rcp_f32_e32 v72, v72
	v_pk_fma_f32 v[66:67], v[138:139], v[86:87], v[66:67]
	v_add_f32_e32 v73, 1.0, v73
	v_rcp_f32_e32 v73, v73
	v_pk_add_f32 v[66:67], v[142:143], v[66:67]
	v_pk_add_f32 v[70:71], v[130:131], v[70:71]
	v_pk_mul_f32 v[64:65], v[64:65], v[72:73]
	s_nop 0
	v_pk_mul_f32 v[64:65], v[68:69], v[64:65]
	v_mul_f32_e32 v68, 0xbfb8aa3b, v66
	v_exp_f32_e32 v68, v68
	v_mul_f32_e32 v69, 0xbfb8aa3b, v67
	v_exp_f32_e32 v69, v69
	v_cvt_pk_bf16_f32 v64, v64, v65
	v_add_f32_e32 v65, 1.0, v68
	v_rcp_f32_e32 v68, v65
	v_add_f32_e32 v65, 1.0, v69
	v_rcp_f32_e32 v69, v65
	v_mov_b32_dpp v118, v58 row_shr:1 row_mask:0xf bank_mask:0xf bound_ctrl:1
	v_cndmask_b32_e64 v117, v62, v54, s[6:7]
	v_pk_mul_f32 v[66:67], v[66:67], v[68:69]
	s_nop 0
	v_mov_b32_dpp v120, v117 row_ror:15 row_mask:0xf bank_mask:0xf
	v_pk_mul_f32 v[66:67], v[70:71], v[66:67]
	v_cndmask_b32_e64 v117, v58, v50, s[6:7]
	v_cvt_pk_bf16_f32 v65, v66, v67
	global_store_dwordx2 v[104:105], v[64:65], off
	v_mov_b32_dpp v122, v117 row_ror:15 row_mask:0xf bank_mask:0xf
	v_cndmask_b32_e64 v123, v63, v55, s[6:7]
	v_mov_b32_dpp v117, v63 row_shr:1 row_mask:0xf bank_mask:0xf bound_ctrl:1
	v_cndmask_b32_e64 v126, v59, v51, s[6:7]
	v_pk_mul_f32 v[124:125], v[56:57], v[234:235]
	s_nop 0
	v_pk_fma_f32 v[108:109], v[230:231], v[108:109], v[124:125]
	v_mov_b32_dpp v119, v59 row_shr:1 row_mask:0xf bank_mask:0xf bound_ctrl:1
	v_pk_fma_f32 v[108:109], v[238:239], v[114:115], v[108:109]
	s_nop 0
	v_pk_add_f32 v[108:109], v[242:243], v[108:109]
	v_pk_mul_f32 v[128:129], v[60:61], v[246:247]
	v_mul_f32_e32 v114, 0xbfb8aa3b, v108
	v_mul_f32_e32 v125, 0xbfb8aa3b, v109
	v_exp_f32_e32 v124, v114
	v_exp_f32_e32 v125, v125
	v_pk_fma_f32 v[106:107], v[250:251], v[106:107], v[128:129]
	v_mov_b32_dpp v121, v123 row_ror:15 row_mask:0xf bank_mask:0xf
	v_add_f32_e32 v124, 1.0, v124
	v_add_f32_e32 v125, 1.0, v125
	v_rcp_f32_e32 v124, v124
	v_rcp_f32_e32 v125, v125
	v_pk_fma_f32 v[106:107], v[190:191], v[110:111], v[106:107]
	v_pk_mul_f32 v[114:115], v[58:59], v[236:237]
	v_pk_add_f32 v[106:107], v[180:181], v[106:107]
	v_pk_mul_f32 v[108:109], v[108:109], v[124:125]
	v_mov_b32_dpp v123, v126 row_ror:15 row_mask:0xf bank_mask:0xf
	v_pk_mul_f32 v[106:107], v[106:107], v[108:109]
	v_pk_fma_f32 v[108:109], v[232:233], v[118:119], v[114:115]
	v_cvt_pk_bf16_f32 v106, v106, v107
	v_pk_fma_f32 v[108:109], v[240:241], v[122:123], v[108:109]
	v_pk_mul_f32 v[126:127], v[62:63], v[248:249]
	v_pk_add_f32 v[108:109], v[244:245], v[108:109]
	v_pk_fma_f32 v[114:115], v[252:253], v[116:117], v[126:127]
	v_mul_f32_e32 v110, 0xbfb8aa3b, v108
	v_exp_f32_e32 v110, v110
	v_mul_f32_e32 v111, 0xbfb8aa3b, v109
	v_exp_f32_e32 v111, v111
	v_pk_fma_f32 v[114:115], v[192:193], v[120:121], v[114:115]
	v_add_f32_e32 v107, 1.0, v110
	v_rcp_f32_e32 v110, v107
	v_add_f32_e32 v107, 1.0, v111
	v_rcp_f32_e32 v111, v107
	v_pk_add_f32 v[114:115], v[182:183], v[114:115]
	v_pk_mul_f32 v[116:117], v[48:49], v[234:235]
	v_cndmask_b32_e64 v118, v51, v43, s[6:7]
	v_pk_mul_f32 v[108:109], v[108:109], v[110:111]
	v_cndmask_b32_e64 v110, v49, v41, s[6:7]
	v_pk_mul_f32 v[108:109], v[114:115], v[108:109]
	v_cndmask_b32_e64 v111, v54, v46, s[6:7]
	v_cvt_pk_bf16_f32 v107, v108, v109
	global_store_dwordx2 v[168:169], v[106:107], off offset:32
	v_cndmask_b32_e64 v106, v52, v60, s[4:5]
	v_cndmask_b32_e64 v107, v52, v44, s[6:7]
	s_nop 0
	v_mov_b32_dpp v60, v106 row_ror:1 row_mask:0xf bank_mask:0xf
	v_cndmask_b32_e64 v106, v48, v56, s[4:5]
	v_cndmask_b32_e64 v109, v53, v45, s[6:7]
	s_nop 0
	v_mov_b32_dpp v56, v106 row_ror:1 row_mask:0xf bank_mask:0xf
	v_cndmask_b32_e64 v115, v55, v47, s[6:7]
	v_pk_mul_f32 v[120:121], v[52:53], v[246:247]
	v_mov_b32_dpp v106, v107 row_ror:15 row_mask:0xf bank_mask:0xf
	v_cndmask_b32_e64 v107, v48, v40, s[6:7]
	s_nop 1
	v_mov_b32_dpp v108, v107 row_ror:15 row_mask:0xf bank_mask:0xf
	v_cndmask_b32_e64 v107, v53, v61, s[4:5]
	s_nop 1
	v_mov_b32_dpp v61, v107 row_ror:1 row_mask:0xf bank_mask:0xf
	v_cndmask_b32_e64 v107, v49, v57, s[4:5]
	v_pk_fma_f32 v[60:61], v[250:251], v[60:61], v[120:121]
	s_nop 0
	v_mov_b32_dpp v57, v107 row_ror:1 row_mask:0xf bank_mask:0xf
	v_pk_fma_f32 v[56:57], v[230:231], v[56:57], v[116:117]
	s_nop 0
	v_mov_b32_dpp v107, v109 row_ror:15 row_mask:0xf bank_mask:0xf
; __device__ __forceinline__ void st_bf4(bf16_t* p, f32x4 v) { u32x2 w; w.x = pk2(v[0], v[1]); w.y = pk2(v[2], v[3]); *(u32x2*)p = w; }
; __device__ __forceinline__ float sigmoidf_(float x) { return __builtin_amdgcn_rcpf(1.f + __expf(-x)); }
; __device__ __forceinline__ float dpp_ror1(float v) { return __int_as_float(__builtin_amdgcn_update_dpp(0, __float_as_int(v), 0x121, 0xf, 0xf, false)); }
; __device__ __forceinline__ float dpp_rol1(float v) { return __int_as_float(__builtin_amdgcn_update_dpp(0, __float_as_int(v), 0x12F, 0xf, 0xf, false)); }
;     __device__ __forceinline__ void tile(const f32x4 (&acc)[2][2][4][2], const Unit& u, int wr, int wc, int fr, int fq) const {
;     ...
;         for (int n = 0; n < 2; ++n) {
;             const int cv = 128 * u.pn + 32 * wc + 16 * n + 4 * fq, cg = FF + cv;
;             const f32x4 wv0 = *(const f32x4*)(cw + cv), wv1 = *(const f32x4*)(cw + F2 + cv), wv2 = *(const f32x4*)(cw + 2 * F2 + cv), bv = *(const f32x4*)(cb + cv);
;             const f32x4 wg0 = *(const f32x4*)(cw + cg), wg1 = *(const f32x4*)(cw + F2 + cg), wg2 = *(const f32x4*)(cw + 2 * F2 + cg), bg = *(const f32x4*)(cb + cg);
; #pragma unroll
;             for (int ai = 0; ai < 2; ++ai)
; #pragma unroll
;                 for (int m = 0; m < 4; ++m) {
;                     f32x4 r;
; #pragma unroll
;                     for (int i = 0; i < 4; ++i) {
;                         const float xv = acc[ai][0][m][n][i], xg = acc[ai][1][m][n][i];
;                         const float uv = m > 0 ? acc[ai][0][m > 0 ? m - 1 : 0][n][i] : 0.f, ug = m > 0 ? acc[ai][1][m > 0 ? m - 1 : 0][n][i] : 0.f;
;                         const float dv = m < 3 ? acc[ai][0][m < 3 ? m + 1 : 3][n][i] : 0.f, dg = m < 3 ? acc[ai][1][m < 3 ? m + 1 : 3][n][i] : 0.f;
;                         const float pv = dpp_ror1(fr == 15 ? uv : xv), pg = dpp_ror1(fr == 15 ? ug : xg);
;                         const float nv = dpp_rol1(fr == 0 ? dv : xv), ng = dpp_rol1(fr == 0 ? dg : xg);
;                         const float yv = wv0[i] * pv + wv1[i] * xv + wv2[i] * nv + bv[i];
;                         const float yg = wg0[i] * pg + wg1[i] * xg + wg2[i] * ng + bg[i];
;                         r[i] = yg * sigmoidf_(yg) * yv;
;                     }
;                     st_bf4(ACT + (size_t)(u.pm * BM + ai * HALF + wr * 64 + m * 16 + fr) * FF + cv, r);
;                 }
	v_pk_fma_f32 v[60:61], v[190:191], v[106:107], v[60:61]
	v_pk_mul_f32 v[106:107], v[40:41], v[234:235]
	v_mov_b32_dpp v109, v110 row_ror:15 row_mask:0xf bank_mask:0xf
	v_pk_fma_f32 v[56:57], v[238:239], v[108:109], v[56:57]
	v_cndmask_b32_e64 v110, v54, v62, s[4:5]
	v_pk_add_f32 v[56:57], v[242:243], v[56:57]
	s_nop 0
	v_mul_f32_e32 v108, 0xbfb8aa3b, v56
	v_mul_f32_e32 v117, 0xbfb8aa3b, v57
	v_mov_b32_dpp v62, v110 row_ror:1 row_mask:0xf bank_mask:0xf
	v_cndmask_b32_e64 v110, v50, v58, s[4:5]
	v_exp_f32_e32 v116, v108
	v_exp_f32_e32 v117, v117
	v_mov_b32_dpp v58, v110 row_ror:1 row_mask:0xf bank_mask:0xf
	v_add_f32_e32 v116, 1.0, v116
	v_add_f32_e32 v117, 1.0, v117
	v_mov_b32_dpp v110, v111 row_ror:15 row_mask:0xf bank_mask:0xf
	v_cndmask_b32_e64 v111, v50, v42, s[6:7]
	v_rcp_f32_e32 v116, v116
	v_rcp_f32_e32 v117, v117
	v_mov_b32_dpp v114, v111 row_ror:15 row_mask:0xf bank_mask:0xf
	v_cndmask_b32_e64 v111, v55, v63, s[4:5]
	v_pk_mul_f32 v[108:109], v[50:51], v[236:237]
	v_pk_add_f32 v[60:61], v[180:181], v[60:61]
	v_mov_b32_dpp v63, v111 row_ror:1 row_mask:0xf bank_mask:0xf
	v_cndmask_b32_e64 v111, v51, v59, s[4:5]
	v_pk_mul_f32 v[56:57], v[56:57], v[116:117]
	s_nop 0
	v_mov_b32_dpp v59, v111 row_ror:1 row_mask:0xf bank_mask:0xf
	v_pk_fma_f32 v[58:59], v[232:233], v[58:59], v[108:109]
	v_pk_mul_f32 v[56:57], v[60:61], v[56:57]
	v_mov_b32_dpp v111, v115 row_ror:15 row_mask:0xf bank_mask:0xf
	v_cvt_pk_bf16_f32 v56, v56, v57
	v_cndmask_b32_e64 v108, v43, v35, s[6:7]
	v_mov_b32_dpp v115, v118 row_ror:15 row_mask:0xf bank_mask:0xf
	v_pk_fma_f32 v[58:59], v[240:241], v[114:115], v[58:59]
	v_pk_mul_f32 v[118:119], v[54:55], v[248:249]
	v_pk_add_f32 v[58:59], v[244:245], v[58:59]
	v_pk_fma_f32 v[62:63], v[252:253], v[62:63], v[118:119]
	v_mul_f32_e32 v60, 0xbfb8aa3b, v58
	v_exp_f32_e32 v60, v60
	v_mul_f32_e32 v61, 0xbfb8aa3b, v59
	v_exp_f32_e32 v61, v61
	v_pk_fma_f32 v[62:63], v[192:193], v[110:111], v[62:63]
	v_add_f32_e32 v57, 1.0, v60
	v_rcp_f32_e32 v60, v57
	v_add_f32_e32 v57, 1.0, v61
	v_rcp_f32_e32 v61, v57
	v_pk_add_f32 v[62:63], v[182:183], v[62:63]
	v_pk_mul_f32 v[110:111], v[44:45], v[246:247]
	v_pk_mul_f32 v[58:59], v[58:59], v[60:61]
	s_nop 0
	v_pk_mul_f32 v[58:59], v[62:63], v[58:59]
	v_cndmask_b32_e64 v60, v41, v33, s[6:7]
	v_cvt_pk_bf16_f32 v57, v58, v59
	global_store_dwordx2 v[152:153], v[56:57], off offset:32
	v_cndmask_b32_e64 v56, v44, v52, s[4:5]
	v_cndmask_b32_e64 v57, v44, v36, s[6:7]
	s_nop 0
	v_mov_b32_dpp v52, v56 row_ror:1 row_mask:0xf bank_mask:0xf
	v_cndmask_b32_e64 v56, v40, v48, s[4:5]
	v_cndmask_b32_e64 v59, v45, v37, s[6:7]
	v_cndmask_b32_e64 v61, v46, v38, s[6:7]
	v_mov_b32_dpp v48, v56 row_ror:1 row_mask:0xf bank_mask:0xf
	v_cndmask_b32_e64 v63, v47, v39, s[6:7]
	v_mov_b32_dpp v56, v57 row_ror:15 row_mask:0xf bank_mask:0xf
	v_cndmask_b32_e64 v57, v40, v32, s[6:7]
	s_nop 1
	v_mov_b32_dpp v58, v57 row_ror:15 row_mask:0xf bank_mask:0xf
	v_cndmask_b32_e64 v57, v45, v53, s[4:5]
	s_nop 1
	v_mov_b32_dpp v53, v57 row_ror:1 row_mask:0xf bank_mask:0xf
	v_cndmask_b32_e64 v57, v41, v49, s[4:5]
	v_pk_fma_f32 v[52:53], v[250:251], v[52:53], v[110:111]
	s_nop 0
	v_mov_b32_dpp v49, v57 row_ror:1 row_mask:0xf bank_mask:0xf
	v_pk_fma_f32 v[48:49], v[230:231], v[48:49], v[106:107]
	s_nop 0
	v_mov_b32_dpp v57, v59 row_ror:15 row_mask:0xf bank_mask:0xf
	v_pk_fma_f32 v[52:53], v[190:191], v[56:57], v[52:53]
	v_cndmask_b32_e64 v56, v35, 0, s[6:7]
	v_mov_b32_dpp v59, v60 row_ror:15 row_mask:0xf bank_mask:0xf
	v_pk_fma_f32 v[48:49], v[238:239], v[58:59], v[48:49]
	v_cndmask_b32_e64 v60, v46, v54, s[4:5]
	v_pk_add_f32 v[48:49], v[242:243], v[48:49]
	s_nop 0
	v_mul_f32_e32 v58, 0xbfb8aa3b, v48
	v_mul_f32_e32 v107, 0xbfb8aa3b, v49
	v_mov_b32_dpp v54, v60 row_ror:1 row_mask:0xf bank_mask:0xf
	v_cndmask_b32_e64 v60, v42, v50, s[4:5]
	v_exp_f32_e32 v106, v58
	v_exp_f32_e32 v107, v107
	v_mov_b32_dpp v50, v60 row_ror:1 row_mask:0xf bank_mask:0xf
	v_add_f32_e32 v106, 1.0, v106
	v_add_f32_e32 v107, 1.0, v107
	v_mov_b32_dpp v60, v61 row_ror:15 row_mask:0xf bank_mask:0xf
	v_cndmask_b32_e64 v61, v42, v34, s[6:7]
	v_rcp_f32_e32 v106, v106
	v_rcp_f32_e32 v107, v107
	v_mov_b32_dpp v62, v61 row_ror:15 row_mask:0xf bank_mask:0xf
	v_cndmask_b32_e64 v61, v47, v55, s[4:5]
	v_pk_mul_f32 v[58:59], v[42:43], v[236:237]
	v_pk_add_f32 v[52:53], v[180:181], v[52:53]
	v_mov_b32_dpp v55, v61 row_ror:1 row_mask:0xf bank_mask:0xf
	v_cndmask_b32_e64 v61, v43, v51, s[4:5]
	v_pk_mul_f32 v[48:49], v[48:49], v[106:107]
	s_nop 0
	v_mov_b32_dpp v51, v61 row_ror:1 row_mask:0xf bank_mask:0xf
	v_pk_fma_f32 v[50:51], v[232:233], v[50:51], v[58:59]
	v_pk_mul_f32 v[48:49], v[52:53], v[48:49]
	v_mov_b32_dpp v61, v63 row_ror:15 row_mask:0xf bank_mask:0xf
	v_cvt_pk_bf16_f32 v48, v48, v49
	s_nop 0
	v_mov_b32_dpp v63, v108 row_ror:15 row_mask:0xf bank_mask:0xf
	v_pk_fma_f32 v[50:51], v[240:241], v[62:63], v[50:51]
	v_pk_mul_f32 v[108:109], v[46:47], v[248:249]
	v_pk_add_f32 v[50:51], v[244:245], v[50:51]
	v_pk_fma_f32 v[54:55], v[252:253], v[54:55], v[108:109]
	v_mul_f32_e32 v52, 0xbfb8aa3b, v50
	v_exp_f32_e32 v52, v52
	v_mul_f32_e32 v53, 0xbfb8aa3b, v51
	v_exp_f32_e32 v53, v53
	v_pk_fma_f32 v[54:55], v[192:193], v[60:61], v[54:55]
	v_add_f32_e32 v49, 1.0, v52
	v_rcp_f32_e32 v52, v49
	v_add_f32_e32 v49, 1.0, v53
	v_rcp_f32_e32 v53, v49
	v_pk_add_f32 v[54:55], v[182:183], v[54:55]
	v_pk_mul_f32 v[50:51], v[50:51], v[52:53]
	s_nop 0
	v_pk_mul_f32 v[50:51], v[54:55], v[50:51]
	v_cndmask_b32_e64 v52, v33, 0, s[6:7]
	v_cvt_pk_bf16_f32 v49, v50, v51
	global_store_dwordx2 v[112:113], v[48:49], off offset:32
	v_cndmask_b32_e64 v48, v36, v44, s[4:5]
	s_nop 1
; __device__ __forceinline__ void st_bf4(bf16_t* p, f32x4 v) { u32x2 w; w.x = pk2(v[0], v[1]); w.y = pk2(v[2], v[3]); *(u32x2*)p = w; }
; __device__ __forceinline__ float sigmoidf_(float x) { return __builtin_amdgcn_rcpf(1.f + __expf(-x)); }
; __device__ __forceinline__ float dpp_ror1(float v) { return __int_as_float(__builtin_amdgcn_update_dpp(0, __float_as_int(v), 0x121, 0xf, 0xf, false)); }
; __device__ __forceinline__ float dpp_rol1(float v) { return __int_as_float(__builtin_amdgcn_update_dpp(0, __float_as_int(v), 0x12F, 0xf, 0xf, false)); }
;     __device__ __forceinline__ void tile(const f32x4 (&acc)[2][2][4][2], const Unit& u, int wr, int wc, int fr, int fq) const {
;     ...
;         for (int n = 0; n < 2; ++n) {
;             const int cv = 128 * u.pn + 32 * wc + 16 * n + 4 * fq, cg = FF + cv;
;             const f32x4 wv0 = *(const f32x4*)(cw + cv), wv1 = *(const f32x4*)(cw + F2 + cv), wv2 = *(const f32x4*)(cw + 2 * F2 + cv), bv = *(const f32x4*)(cb + cv);
;             const f32x4 wg0 = *(const f32x4*)(cw + cg), wg1 = *(const f32x4*)(cw + F2 + cg), wg2 = *(const f32x4*)(cw + 2 * F2 + cg), bg = *(const f32x4*)(cb + cg);
; #pragma unroll
;             for (int ai = 0; ai < 2; ++ai)
; #pragma unroll
;                 for (int m = 0; m < 4; ++m) {
;                     f32x4 r;
; #pragma unroll
;                     for (int i = 0; i < 4; ++i) {
;                         const float xv = acc[ai][0][m][n][i], xg = acc[ai][1][m][n][i];
;                         const float uv = m > 0 ? acc[ai][0][m > 0 ? m - 1 : 0][n][i] : 0.f, ug = m > 0 ? acc[ai][1][m > 0 ? m - 1 : 0][n][i] : 0.f;
;                         const float dv = m < 3 ? acc[ai][0][m < 3 ? m + 1 : 3][n][i] : 0.f, dg = m < 3 ? acc[ai][1][m < 3 ? m + 1 : 3][n][i] : 0.f;
;                         const float pv = dpp_ror1(fr == 15 ? uv : xv), pg = dpp_ror1(fr == 15 ? ug : xg);
;                         const float nv = dpp_rol1(fr == 0 ? dv : xv), ng = dpp_rol1(fr == 0 ? dg : xg);
;                         const float yv = wv0[i] * pv + wv1[i] * xv + wv2[i] * nv + bv[i];
;                         const float yg = wg0[i] * pg + wg1[i] * xg + wg2[i] * ng + bg[i];
;                         r[i] = yg * sigmoidf_(yg) * yv;
;                     }
;                     st_bf4(ACT + (size_t)(u.pm * BM + ai * HALF + wr * 64 + m * 16 + fr) * FF + cv, r);
;                 }
	v_mov_b32_dpp v44, v48 row_ror:1 row_mask:0xf bank_mask:0xf
	v_cndmask_b32_e64 v48, v32, v40, s[4:5]
	v_cndmask_b32_e64 v51, v37, 0, s[6:7]
	s_nop 0
	v_mov_b32_dpp v40, v48 row_ror:1 row_mask:0xf bank_mask:0xf
	v_mov_b32_dpp v48, v36 row_shl:1 row_mask:0xf bank_mask:0xf bound_ctrl:1
	s_nop 1
	v_mov_b32_dpp v50, v32 row_shl:1 row_mask:0xf bank_mask:0xf bound_ctrl:1
	v_cndmask_b32_e64 v49, v37, v45, s[4:5]
	v_pk_mul_f32 v[36:37], v[36:37], v[246:247]
	s_nop 0
	v_mov_b32_dpp v45, v49 row_ror:1 row_mask:0xf bank_mask:0xf
	v_cndmask_b32_e64 v49, v33, v41, s[4:5]
	v_pk_mul_f32 v[32:33], v[32:33], v[234:235]
	v_pk_fma_f32 v[36:37], v[250:251], v[44:45], v[36:37]
	v_mov_b32_dpp v41, v49 row_ror:1 row_mask:0xf bank_mask:0xf
	v_pk_fma_f32 v[32:33], v[230:231], v[40:41], v[32:33]
	v_mov_b32_dpp v49, v51 row_ror:15 row_mask:0xf bank_mask:0xf
	v_pk_fma_f32 v[36:37], v[190:191], v[48:49], v[36:37]
	v_pk_mul_f32 v[48:49], v[24:25], v[234:235]
	v_mov_b32_dpp v51, v52 row_ror:15 row_mask:0xf bank_mask:0xf
	v_pk_fma_f32 v[32:33], v[238:239], v[50:51], v[32:33]
	v_cndmask_b32_e64 v52, v38, v46, s[4:5]
	v_pk_add_f32 v[32:33], v[242:243], v[32:33]
	s_nop 0
	v_mul_f32_e32 v40, 0xbfb8aa3b, v32
	v_mul_f32_e32 v41, 0xbfb8aa3b, v33
	v_mov_b32_dpp v46, v52 row_ror:1 row_mask:0xf bank_mask:0xf
	v_cndmask_b32_e64 v52, v34, v42, s[4:5]
	v_exp_f32_e32 v40, v40
	v_exp_f32_e32 v41, v41
	v_mov_b32_dpp v42, v52 row_ror:1 row_mask:0xf bank_mask:0xf
	v_add_f32_e32 v40, 1.0, v40
	v_add_f32_e32 v41, 1.0, v41
	v_mov_b32_dpp v52, v38 row_shl:1 row_mask:0xf bank_mask:0xf bound_ctrl:1
	v_rcp_f32_e32 v40, v40
	v_rcp_f32_e32 v41, v41
	v_mov_b32_dpp v54, v34 row_shl:1 row_mask:0xf bank_mask:0xf bound_ctrl:1
	v_cndmask_b32_e64 v53, v39, v47, s[4:5]
	v_pk_add_f32 v[36:37], v[180:181], v[36:37]
	v_pk_mul_f32 v[32:33], v[32:33], v[40:41]
	v_mov_b32_dpp v47, v53 row_ror:1 row_mask:0xf bank_mask:0xf
	v_cndmask_b32_e64 v53, v35, v43, s[4:5]
	v_pk_mul_f32 v[34:35], v[34:35], v[236:237]
	v_pk_mul_f32 v[32:33], v[36:37], v[32:33]
	v_mov_b32_dpp v43, v53 row_ror:1 row_mask:0xf bank_mask:0xf
	v_pk_fma_f32 v[34:35], v[232:233], v[42:43], v[34:35]
	v_cvt_pk_bf16_f32 v32, v32, v33
	v_mov_b32_dpp v53, v39 row_shl:1 row_mask:0xf bank_mask:0xf bound_ctrl:1
	v_pk_mul_f32 v[38:39], v[38:39], v[248:249]
	v_cndmask_b32_e64 v40, v25, v17, s[6:7]
	v_mov_b32_dpp v55, v56 row_ror:15 row_mask:0xf bank_mask:0xf
	v_pk_fma_f32 v[34:35], v[240:241], v[54:55], v[34:35]
	v_pk_fma_f32 v[38:39], v[252:253], v[46:47], v[38:39]
	v_pk_add_f32 v[34:35], v[244:245], v[34:35]
	v_pk_fma_f32 v[38:39], v[192:193], v[52:53], v[38:39]
	v_mul_f32_e32 v36, 0xbfb8aa3b, v34
	v_exp_f32_e32 v36, v36
	v_mul_f32_e32 v37, 0xbfb8aa3b, v35
	v_exp_f32_e32 v37, v37
	v_pk_add_f32 v[38:39], v[182:183], v[38:39]
	v_add_f32_e32 v33, 1.0, v36
	v_rcp_f32_e32 v36, v33
	v_add_f32_e32 v33, 1.0, v37
	v_rcp_f32_e32 v37, v33
	s_nop 0
	v_pk_mul_f32 v[34:35], v[34:35], v[36:37]
	s_nop 0
	v_pk_mul_f32 v[34:35], v[38:39], v[34:35]
	s_nop 0
	v_cvt_pk_bf16_f32 v33, v34, v35
	global_store_dwordx2 v[96:97], v[32:33], off offset:32
	v_mov_b32_dpp v32, v28 row_shr:1 row_mask:0xf bank_mask:0xf bound_ctrl:1
	v_cndmask_b32_e64 v39, v29, v21, s[6:7]
	v_mov_b32_dpp v34, v24 row_shr:1 row_mask:0xf bank_mask:0xf bound_ctrl:1
	v_cndmask_b32_e64 v33, v28, v20, s[6:7]
	v_pk_mul_f32 v[52:53], v[28:29], v[246:247]
	s_nop 0
	v_mov_b32_dpp v36, v33 row_ror:15 row_mask:0xf bank_mask:0xf
	v_cndmask_b32_e64 v33, v24, v16, s[6:7]
	v_cndmask_b32_e64 v47, v31, v23, s[6:7]
	s_nop 0
	v_mov_b32_dpp v38, v33 row_ror:15 row_mask:0xf bank_mask:0xf
	v_cndmask_b32_e64 v50, v27, v19, s[6:7]
	s_nop 0
	v_mov_b32_dpp v33, v29 row_shr:1 row_mask:0xf bank_mask:0xf bound_ctrl:1
	v_pk_fma_f32 v[32:33], v[250:251], v[32:33], v[52:53]
	s_nop 0
	v_mov_b32_dpp v35, v25 row_shr:1 row_mask:0xf bank_mask:0xf bound_ctrl:1
	v_pk_fma_f32 v[34:35], v[230:231], v[34:35], v[48:49]
	s_nop 0
	v_mov_b32_dpp v37, v39 row_ror:15 row_mask:0xf bank_mask:0xf
	v_pk_fma_f32 v[32:33], v[190:191], v[36:37], v[32:33]
	s_nop 0
	v_mov_b32_dpp v39, v40 row_ror:15 row_mask:0xf bank_mask:0xf
	v_pk_fma_f32 v[34:35], v[238:239], v[38:39], v[34:35]
	s_nop 0
	v_pk_add_f32 v[34:35], v[242:243], v[34:35]
	v_pk_add_f32 v[32:33], v[180:181], v[32:33]
	v_mul_f32_e32 v38, 0xbfb8aa3b, v34
	v_mul_f32_e32 v49, 0xbfb8aa3b, v35
	v_exp_f32_e32 v48, v38
	v_exp_f32_e32 v49, v49
	v_mov_b32_dpp v40, v30 row_shr:1 row_mask:0xf bank_mask:0xf bound_ctrl:1
	v_add_f32_e32 v48, 1.0, v48
	v_add_f32_e32 v49, 1.0, v49
	v_mov_b32_dpp v42, v26 row_shr:1 row_mask:0xf bank_mask:0xf bound_ctrl:1
	v_cndmask_b32_e64 v41, v30, v22, s[6:7]
	v_rcp_f32_e32 v48, v48
	v_rcp_f32_e32 v49, v49
	v_mov_b32_dpp v44, v41 row_ror:15 row_mask:0xf bank_mask:0xf
	v_cndmask_b32_e64 v41, v26, v18, s[6:7]
	v_pk_mul_f32 v[38:39], v[26:27], v[236:237]
	v_pk_mul_f32 v[34:35], v[34:35], v[48:49]
	v_mov_b32_dpp v46, v41 row_ror:15 row_mask:0xf bank_mask:0xf
	v_pk_mul_f32 v[32:33], v[32:33], v[34:35]
	s_nop 0
	v_mov_b32_dpp v41, v31 row_shr:1 row_mask:0xf bank_mask:0xf bound_ctrl:1
	v_cvt_pk_bf16_f32 v32, v32, v33
	s_nop 0
	v_mov_b32_dpp v43, v27 row_shr:1 row_mask:0xf bank_mask:0xf bound_ctrl:1
	v_pk_fma_f32 v[34:35], v[232:233], v[42:43], v[38:39]
	v_cndmask_b32_e64 v42, v19, v11, s[6:7]
	v_mov_b32_dpp v45, v47 row_ror:15 row_mask:0xf bank_mask:0xf
	s_nop 1
	v_mov_b32_dpp v47, v50 row_ror:15 row_mask:0xf bank_mask:0xf
	v_pk_fma_f32 v[34:35], v[240:241], v[46:47], v[34:35]
	v_pk_mul_f32 v[50:51], v[30:31], v[248:249]
	v_pk_add_f32 v[34:35], v[244:245], v[34:35]
	v_pk_fma_f32 v[38:39], v[252:253], v[40:41], v[50:51]
	v_mul_f32_e32 v36, 0xbfb8aa3b, v34
	v_exp_f32_e32 v36, v36
; __device__ __forceinline__ void st_bf4(bf16_t* p, f32x4 v) { u32x2 w; w.x = pk2(v[0], v[1]); w.y = pk2(v[2], v[3]); *(u32x2*)p = w; }
; __device__ __forceinline__ float sigmoidf_(float x) { return __builtin_amdgcn_rcpf(1.f + __expf(-x)); }
; __device__ __forceinline__ float dpp_ror1(float v) { return __int_as_float(__builtin_amdgcn_update_dpp(0, __float_as_int(v), 0x121, 0xf, 0xf, false)); }
; __device__ __forceinline__ float dpp_rol1(float v) { return __int_as_float(__builtin_amdgcn_update_dpp(0, __float_as_int(v), 0x12F, 0xf, 0xf, false)); }
;     __device__ __forceinline__ void tile(const f32x4 (&acc)[2][2][4][2], const Unit& u, int wr, int wc, int fr, int fq) const {
;     ...
;         for (int n = 0; n < 2; ++n) {
;             const int cv = 128 * u.pn + 32 * wc + 16 * n + 4 * fq, cg = FF + cv;
;             const f32x4 wv0 = *(const f32x4*)(cw + cv), wv1 = *(const f32x4*)(cw + F2 + cv), wv2 = *(const f32x4*)(cw + 2 * F2 + cv), bv = *(const f32x4*)(cb + cv);
;             const f32x4 wg0 = *(const f32x4*)(cw + cg), wg1 = *(const f32x4*)(cw + F2 + cg), wg2 = *(const f32x4*)(cw + 2 * F2 + cg), bg = *(const f32x4*)(cb + cg);
; #pragma unroll
;             for (int ai = 0; ai < 2; ++ai)
; #pragma unroll
;                 for (int m = 0; m < 4; ++m) {
;                     f32x4 r;
; #pragma unroll
;                     for (int i = 0; i < 4; ++i) {
;                         const float xv = acc[ai][0][m][n][i], xg = acc[ai][1][m][n][i];
;                         const float uv = m > 0 ? acc[ai][0][m > 0 ? m - 1 : 0][n][i] : 0.f, ug = m > 0 ? acc[ai][1][m > 0 ? m - 1 : 0][n][i] : 0.f;
;                         const float dv = m < 3 ? acc[ai][0][m < 3 ? m + 1 : 3][n][i] : 0.f, dg = m < 3 ? acc[ai][1][m < 3 ? m + 1 : 3][n][i] : 0.f;
;                         const float pv = dpp_ror1(fr == 15 ? uv : xv), pg = dpp_ror1(fr == 15 ? ug : xg);
;                         const float nv = dpp_rol1(fr == 0 ? dv : xv), ng = dpp_rol1(fr == 0 ? dg : xg);
;                         const float yv = wv0[i] * pv + wv1[i] * xv + wv2[i] * nv + bv[i];
;                         const float yg = wg0[i] * pg + wg1[i] * xg + wg2[i] * ng + bg[i];
;                         r[i] = yg * sigmoidf_(yg) * yv;
;                     }
;                     st_bf4(ACT + (size_t)(u.pm * BM + ai * HALF + wr * 64 + m * 16 + fr) * FF + cv, r);
;                 }
	v_mul_f32_e32 v37, 0xbfb8aa3b, v35
	v_exp_f32_e32 v37, v37
	v_pk_fma_f32 v[38:39], v[192:193], v[44:45], v[38:39]
	v_add_f32_e32 v33, 1.0, v36
	v_rcp_f32_e32 v36, v33
	v_add_f32_e32 v33, 1.0, v37
	v_rcp_f32_e32 v37, v33
	v_pk_add_f32 v[38:39], v[182:183], v[38:39]
	v_pk_mul_f32 v[40:41], v[16:17], v[234:235]
	v_pk_mul_f32 v[44:45], v[20:21], v[246:247]
	v_pk_mul_f32 v[34:35], v[34:35], v[36:37]
	v_cndmask_b32_e64 v36, v17, v9, s[6:7]
	v_pk_mul_f32 v[34:35], v[38:39], v[34:35]
	v_cndmask_b32_e64 v37, v22, v14, s[6:7]
	v_cvt_pk_bf16_f32 v33, v34, v35
	global_store_dwordx2 v[98:99], v[32:33], off offset:32
	v_cndmask_b32_e64 v32, v20, v28, s[4:5]
	v_cndmask_b32_e64 v33, v20, v12, s[6:7]
	s_nop 0
	v_mov_b32_dpp v28, v32 row_ror:1 row_mask:0xf bank_mask:0xf
	v_cndmask_b32_e64 v32, v16, v24, s[4:5]
	v_cndmask_b32_e64 v35, v21, v13, s[6:7]
	s_nop 0
	v_mov_b32_dpp v24, v32 row_ror:1 row_mask:0xf bank_mask:0xf
	v_cndmask_b32_e64 v39, v23, v15, s[6:7]
	s_nop 0
	v_mov_b32_dpp v32, v33 row_ror:15 row_mask:0xf bank_mask:0xf
	v_cndmask_b32_e64 v33, v16, v8, s[6:7]
	s_nop 1
	v_mov_b32_dpp v34, v33 row_ror:15 row_mask:0xf bank_mask:0xf
	v_cndmask_b32_e64 v33, v21, v29, s[4:5]
	s_nop 1
	v_mov_b32_dpp v29, v33 row_ror:1 row_mask:0xf bank_mask:0xf
	v_cndmask_b32_e64 v33, v17, v25, s[4:5]
	v_pk_fma_f32 v[28:29], v[250:251], v[28:29], v[44:45]
	s_nop 0
	v_mov_b32_dpp v25, v33 row_ror:1 row_mask:0xf bank_mask:0xf
	v_pk_fma_f32 v[24:25], v[230:231], v[24:25], v[40:41]
	s_nop 0
	v_mov_b32_dpp v33, v35 row_ror:15 row_mask:0xf bank_mask:0xf
	v_pk_fma_f32 v[28:29], v[190:191], v[32:33], v[28:29]
	v_pk_mul_f32 v[32:33], v[8:9], v[234:235]
	v_mov_b32_dpp v35, v36 row_ror:15 row_mask:0xf bank_mask:0xf
	v_pk_fma_f32 v[24:25], v[238:239], v[34:35], v[24:25]
	v_cndmask_b32_e64 v36, v22, v30, s[4:5]
	v_pk_add_f32 v[24:25], v[242:243], v[24:25]
	s_nop 0
	v_mul_f32_e32 v34, 0xbfb8aa3b, v24
	v_mul_f32_e32 v41, 0xbfb8aa3b, v25
	v_mov_b32_dpp v30, v36 row_ror:1 row_mask:0xf bank_mask:0xf
	v_cndmask_b32_e64 v36, v18, v26, s[4:5]
	v_exp_f32_e32 v40, v34
	v_exp_f32_e32 v41, v41
	v_mov_b32_dpp v26, v36 row_ror:1 row_mask:0xf bank_mask:0xf
	v_add_f32_e32 v40, 1.0, v40
	v_add_f32_e32 v41, 1.0, v41
	v_mov_b32_dpp v36, v37 row_ror:15 row_mask:0xf bank_mask:0xf
	v_cndmask_b32_e64 v37, v18, v10, s[6:7]
	v_rcp_f32_e32 v40, v40
	v_rcp_f32_e32 v41, v41
	v_mov_b32_dpp v38, v37 row_ror:15 row_mask:0xf bank_mask:0xf
	v_cndmask_b32_e64 v37, v23, v31, s[4:5]
	v_pk_mul_f32 v[34:35], v[18:19], v[236:237]
	v_pk_add_f32 v[28:29], v[180:181], v[28:29]
	v_mov_b32_dpp v31, v37 row_ror:1 row_mask:0xf bank_mask:0xf
	v_cndmask_b32_e64 v37, v19, v27, s[4:5]
	v_pk_mul_f32 v[24:25], v[24:25], v[40:41]
	s_nop 0
	v_mov_b32_dpp v27, v37 row_ror:1 row_mask:0xf bank_mask:0xf
	v_pk_fma_f32 v[26:27], v[232:233], v[26:27], v[34:35]
	v_pk_mul_f32 v[24:25], v[28:29], v[24:25]
	v_mov_b32_dpp v37, v39 row_ror:15 row_mask:0xf bank_mask:0xf
	v_cvt_pk_bf16_f32 v24, v24, v25
	v_cndmask_b32_e64 v34, v11, v3, s[6:7]
	v_mov_b32_dpp v39, v42 row_ror:15 row_mask:0xf bank_mask:0xf
	v_pk_fma_f32 v[26:27], v[240:241], v[38:39], v[26:27]
	v_pk_mul_f32 v[42:43], v[22:23], v[248:249]
	v_pk_add_f32 v[26:27], v[244:245], v[26:27]
	v_pk_fma_f32 v[30:31], v[252:253], v[30:31], v[42:43]
	v_mul_f32_e32 v28, 0xbfb8aa3b, v26
	v_exp_f32_e32 v28, v28
	v_mul_f32_e32 v29, 0xbfb8aa3b, v27
	v_exp_f32_e32 v29, v29
	v_pk_fma_f32 v[30:31], v[192:193], v[36:37], v[30:31]
	v_add_f32_e32 v25, 1.0, v28
	v_rcp_f32_e32 v28, v25
	v_add_f32_e32 v25, 1.0, v29
	v_rcp_f32_e32 v29, v25
	v_pk_add_f32 v[30:31], v[182:183], v[30:31]
	v_pk_mul_f32 v[36:37], v[12:13], v[246:247]
	v_pk_mul_f32 v[26:27], v[26:27], v[28:29]
	s_nop 0
	v_pk_mul_f32 v[26:27], v[30:31], v[26:27]
	v_cndmask_b32_e64 v28, v9, v1, s[6:7]
	v_cvt_pk_bf16_f32 v25, v26, v27
	global_store_dwordx2 v[100:101], v[24:25], off offset:32
	v_cndmask_b32_e64 v24, v12, v20, s[4:5]
	v_cndmask_b32_e64 v25, v12, v4, s[6:7]
	s_nop 0
	v_mov_b32_dpp v20, v24 row_ror:1 row_mask:0xf bank_mask:0xf
	v_cndmask_b32_e64 v24, v8, v16, s[4:5]
	v_cndmask_b32_e64 v27, v13, v5, s[6:7]
	v_cndmask_b32_e64 v29, v14, v6, s[6:7]
	v_mov_b32_dpp v16, v24 row_ror:1 row_mask:0xf bank_mask:0xf
	v_cndmask_b32_e64 v31, v15, v7, s[6:7]
	v_mov_b32_dpp v24, v25 row_ror:15 row_mask:0xf bank_mask:0xf
	v_cndmask_b32_e64 v25, v8, v0, s[6:7]
	s_nop 1
	v_mov_b32_dpp v26, v25 row_ror:15 row_mask:0xf bank_mask:0xf
	v_cndmask_b32_e64 v25, v13, v21, s[4:5]
	s_nop 1
	v_mov_b32_dpp v21, v25 row_ror:1 row_mask:0xf bank_mask:0xf
	v_cndmask_b32_e64 v25, v9, v17, s[4:5]
	v_pk_fma_f32 v[20:21], v[250:251], v[20:21], v[36:37]
	s_nop 0
	v_mov_b32_dpp v17, v25 row_ror:1 row_mask:0xf bank_mask:0xf
	v_pk_fma_f32 v[16:17], v[230:231], v[16:17], v[32:33]
	s_nop 0
	v_mov_b32_dpp v25, v27 row_ror:15 row_mask:0xf bank_mask:0xf
	v_pk_fma_f32 v[20:21], v[190:191], v[24:25], v[20:21]
	v_cndmask_b32_e64 v24, v3, 0, s[6:7]
	v_mov_b32_dpp v27, v28 row_ror:15 row_mask:0xf bank_mask:0xf
	v_pk_fma_f32 v[16:17], v[238:239], v[26:27], v[16:17]
	v_cndmask_b32_e64 v28, v14, v22, s[4:5]
; __device__ __forceinline__ void st_bf4(bf16_t* p, f32x4 v) { u32x2 w; w.x = pk2(v[0], v[1]); w.y = pk2(v[2], v[3]); *(u32x2*)p = w; }
; __device__ __forceinline__ float sigmoidf_(float x) { return __builtin_amdgcn_rcpf(1.f + __expf(-x)); }
; __device__ __forceinline__ float dpp_ror1(float v) { return __int_as_float(__builtin_amdgcn_update_dpp(0, __float_as_int(v), 0x121, 0xf, 0xf, false)); }
; __device__ __forceinline__ float dpp_rol1(float v) { return __int_as_float(__builtin_amdgcn_update_dpp(0, __float_as_int(v), 0x12F, 0xf, 0xf, false)); }
;     __device__ __forceinline__ void tile(const f32x4 (&acc)[2][2][4][2], const Unit& u, int wr, int wc, int fr, int fq) const {
;     ...
;         for (int n = 0; n < 2; ++n) {
;             const int cv = 128 * u.pn + 32 * wc + 16 * n + 4 * fq, cg = FF + cv;
;             const f32x4 wv0 = *(const f32x4*)(cw + cv), wv1 = *(const f32x4*)(cw + F2 + cv), wv2 = *(const f32x4*)(cw + 2 * F2 + cv), bv = *(const f32x4*)(cb + cv);
;             const f32x4 wg0 = *(const f32x4*)(cw + cg), wg1 = *(const f32x4*)(cw + F2 + cg), wg2 = *(const f32x4*)(cw + 2 * F2 + cg), bg = *(const f32x4*)(cb + cg);
; #pragma unroll
;             for (int ai = 0; ai < 2; ++ai)
; #pragma unroll
;                 for (int m = 0; m < 4; ++m) {
;                     f32x4 r;
; #pragma unroll
;                     for (int i = 0; i < 4; ++i) {
;                         const float xv = acc[ai][0][m][n][i], xg = acc[ai][1][m][n][i];
;                         const float uv = m > 0 ? acc[ai][0][m > 0 ? m - 1 : 0][n][i] : 0.f, ug = m > 0 ? acc[ai][1][m > 0 ? m - 1 : 0][n][i] : 0.f;
;                         const float dv = m < 3 ? acc[ai][0][m < 3 ? m + 1 : 3][n][i] : 0.f, dg = m < 3 ? acc[ai][1][m < 3 ? m + 1 : 3][n][i] : 0.f;
;                         const float pv = dpp_ror1(fr == 15 ? uv : xv), pg = dpp_ror1(fr == 15 ? ug : xg);
;                         const float nv = dpp_rol1(fr == 0 ? dv : xv), ng = dpp_rol1(fr == 0 ? dg : xg);
;                         const float yv = wv0[i] * pv + wv1[i] * xv + wv2[i] * nv + bv[i];
;                         const float yg = wg0[i] * pg + wg1[i] * xg + wg2[i] * ng + bg[i];
;                         r[i] = yg * sigmoidf_(yg) * yv;
;                     }
;                     st_bf4(ACT + (size_t)(u.pm * BM + ai * HALF + wr * 64 + m * 16 + fr) * FF + cv, r);
;                 }
	v_pk_add_f32 v[16:17], v[242:243], v[16:17]
	s_nop 0
	v_mul_f32_e32 v26, 0xbfb8aa3b, v16
	v_mul_f32_e32 v33, 0xbfb8aa3b, v17
	v_mov_b32_dpp v22, v28 row_ror:1 row_mask:0xf bank_mask:0xf
	v_cndmask_b32_e64 v28, v10, v18, s[4:5]
	v_exp_f32_e32 v32, v26
	v_exp_f32_e32 v33, v33
	v_mov_b32_dpp v18, v28 row_ror:1 row_mask:0xf bank_mask:0xf
	v_add_f32_e32 v32, 1.0, v32
	v_add_f32_e32 v33, 1.0, v33
	v_mov_b32_dpp v28, v29 row_ror:15 row_mask:0xf bank_mask:0xf
	v_cndmask_b32_e64 v29, v10, v2, s[6:7]
	v_rcp_f32_e32 v32, v32
	v_rcp_f32_e32 v33, v33
	v_mov_b32_dpp v30, v29 row_ror:15 row_mask:0xf bank_mask:0xf
	v_cndmask_b32_e64 v29, v15, v23, s[4:5]
	v_pk_mul_f32 v[26:27], v[10:11], v[236:237]
	v_pk_add_f32 v[20:21], v[180:181], v[20:21]
	v_mov_b32_dpp v23, v29 row_ror:1 row_mask:0xf bank_mask:0xf
	v_cndmask_b32_e64 v29, v11, v19, s[4:5]
	v_pk_mul_f32 v[16:17], v[16:17], v[32:33]
	s_nop 0
	v_mov_b32_dpp v19, v29 row_ror:1 row_mask:0xf bank_mask:0xf
	v_pk_fma_f32 v[18:19], v[232:233], v[18:19], v[26:27]
	v_pk_mul_f32 v[16:17], v[20:21], v[16:17]
	v_mov_b32_dpp v29, v31 row_ror:15 row_mask:0xf bank_mask:0xf
	v_cvt_pk_bf16_f32 v16, v16, v17
	s_nop 0
	v_mov_b32_dpp v31, v34 row_ror:15 row_mask:0xf bank_mask:0xf
	v_pk_fma_f32 v[18:19], v[240:241], v[30:31], v[18:19]
	v_pk_mul_f32 v[34:35], v[14:15], v[248:249]
	v_pk_add_f32 v[18:19], v[244:245], v[18:19]
	v_pk_fma_f32 v[22:23], v[252:253], v[22:23], v[34:35]
	v_mul_f32_e32 v20, 0xbfb8aa3b, v18
	v_exp_f32_e32 v20, v20
	v_mul_f32_e32 v21, 0xbfb8aa3b, v19
	v_exp_f32_e32 v21, v21
	v_pk_fma_f32 v[22:23], v[192:193], v[28:29], v[22:23]
	v_add_f32_e32 v17, 1.0, v20
	v_rcp_f32_e32 v20, v17
	v_add_f32_e32 v17, 1.0, v21
	v_rcp_f32_e32 v21, v17
	v_pk_add_f32 v[22:23], v[182:183], v[22:23]
	v_pk_mul_f32 v[18:19], v[18:19], v[20:21]
	s_nop 0
	v_pk_mul_f32 v[18:19], v[22:23], v[18:19]
	v_cndmask_b32_e64 v20, v1, 0, s[6:7]
	v_cvt_pk_bf16_f32 v17, v18, v19
	global_store_dwordx2 v[102:103], v[16:17], off offset:32
	v_cndmask_b32_e64 v16, v4, v12, s[4:5]
	s_nop 1
	v_mov_b32_dpp v12, v16 row_ror:1 row_mask:0xf bank_mask:0xf
	v_cndmask_b32_e64 v16, v0, v8, s[4:5]
	v_cndmask_b32_e64 v19, v5, 0, s[6:7]
	s_nop 0
	v_mov_b32_dpp v8, v16 row_ror:1 row_mask:0xf bank_mask:0xf
	v_cndmask_b32_e64 v23, v7, 0, s[6:7]
	v_mov_b32_dpp v16, v4 row_shl:1 row_mask:0xf bank_mask:0xf bound_ctrl:1
	s_nop 1
	v_mov_b32_dpp v18, v0 row_shl:1 row_mask:0xf bank_mask:0xf bound_ctrl:1
	v_cndmask_b32_e64 v17, v5, v13, s[4:5]
	v_pk_mul_f32 v[4:5], v[4:5], v[246:247]
	s_nop 0
	v_mov_b32_dpp v13, v17 row_ror:1 row_mask:0xf bank_mask:0xf
	v_cndmask_b32_e64 v17, v1, v9, s[4:5]
	v_pk_mul_f32 v[0:1], v[0:1], v[234:235]
	v_pk_fma_f32 v[4:5], v[250:251], v[12:13], v[4:5]
	v_mov_b32_dpp v9, v17 row_ror:1 row_mask:0xf bank_mask:0xf
	v_pk_fma_f32 v[0:1], v[230:231], v[8:9], v[0:1]
	s_nop 0
	v_mov_b32_dpp v17, v19 row_ror:15 row_mask:0xf bank_mask:0xf
	v_pk_fma_f32 v[4:5], v[190:191], v[16:17], v[4:5]
	s_nop 0
	v_mov_b32_dpp v19, v20 row_ror:15 row_mask:0xf bank_mask:0xf
	v_pk_fma_f32 v[0:1], v[238:239], v[18:19], v[0:1]
	v_cndmask_b32_e64 v20, v6, v14, s[4:5]
	v_pk_add_f32 v[0:1], v[242:243], v[0:1]
	s_nop 0
	v_mul_f32_e32 v8, 0xbfb8aa3b, v1
	v_exp_f32_e32 v8, v8
	v_mul_f32_e32 v9, 0xbfb8aa3b, v0
	v_mov_b32_dpp v14, v20 row_ror:1 row_mask:0xf bank_mask:0xf
	v_cndmask_b32_e64 v20, v2, v10, s[4:5]
	v_exp_f32_e32 v18, v9
	v_add_f32_e32 v8, 1.0, v8
	v_mov_b32_dpp v10, v20 row_ror:1 row_mask:0xf bank_mask:0xf
	v_rcp_f32_e32 v9, v8
	v_add_f32_e32 v8, 1.0, v18
	v_mov_b32_dpp v20, v6 row_shl:1 row_mask:0xf bank_mask:0xf bound_ctrl:1
	v_rcp_f32_e32 v8, v8
	v_pk_add_f32 v[4:5], v[180:181], v[4:5]
	v_mov_b32_dpp v22, v2 row_shl:1 row_mask:0xf bank_mask:0xf bound_ctrl:1
	v_cndmask_b32_e64 v21, v7, v15, s[4:5]
	v_pk_mul_f32 v[0:1], v[0:1], v[8:9]
	v_pk_mul_f32 v[6:7], v[6:7], v[248:249]
	v_mov_b32_dpp v15, v21 row_ror:1 row_mask:0xf bank_mask:0xf
	v_cndmask_b32_e64 v21, v3, v11, s[4:5]
	v_pk_mul_f32 v[2:3], v[2:3], v[236:237]
	v_pk_mul_f32 v[0:1], v[4:5], v[0:1]
	v_mov_b32_dpp v11, v21 row_ror:1 row_mask:0xf bank_mask:0xf
	v_pk_fma_f32 v[2:3], v[232:233], v[10:11], v[2:3]
	v_cvt_pk_bf16_f32 v0, v0, v1
	v_mov_b32_dpp v21, v23 row_ror:15 row_mask:0xf bank_mask:0xf
	v_pk_fma_f32 v[6:7], v[252:253], v[14:15], v[6:7]
	s_nop 0
	v_mov_b32_dpp v23, v24 row_ror:15 row_mask:0xf bank_mask:0xf
	v_pk_fma_f32 v[2:3], v[240:241], v[22:23], v[2:3]
	v_pk_fma_f32 v[6:7], v[192:193], v[20:21], v[6:7]
	v_pk_add_f32 v[2:3], v[244:245], v[2:3]
	v_pk_add_f32 v[6:7], v[182:183], v[6:7]
	v_mul_f32_e32 v4, 0xbfb8aa3b, v2
	v_exp_f32_e32 v4, v4
	v_mul_f32_e32 v5, 0xbfb8aa3b, v3
	v_exp_f32_e32 v5, v5
	v_add_f32_e32 v1, 1.0, v4
	v_rcp_f32_e32 v4, v1
	v_add_f32_e32 v1, 1.0, v5
	v_rcp_f32_e32 v5, v1
	s_nop 0
	v_pk_mul_f32 v[2:3], v[2:3], v[4:5]
	s_nop 0
	v_pk_mul_f32 v[2:3], v[6:7], v[2:3]
	s_nop 0
	v_cvt_pk_bf16_f32 v1, v2, v3
	global_store_dwordx2 v[104:105], v[0:1], off offset:32
	s_cbranch_vccnz .LBB0_1795
	s_andn2_b64 vcc, exec, s[2:3]
	s_cbranch_vccnz .LBB0_1794
	s_barrier
	s_branch .LBB0_1794
